# top-256 threshold bisection: wave-uniform search state (threshold, bit, candidate) kept in scalar registers, candidate as scalar compare operand; four vector instructions per pass removed from the dep
# speedup vs baseline: 1.0075x; 1.0033x over previous
; __device__ __forceinline__ void select_group(unsigned char* ws, int r0, const bf16_t* __restrict__ kib, int n, float* sc, SelPre& pre, int nr0, const bf16_t* __restrict__ nkib, int nn) {
;     ...
;     const float* rowl = sc + w * 4096 + lane;
;     const int nreg = (n + 63) >> 6;
;     const int nl = n - lane;
;     unsigned x[64];
; #pragma unroll
;     for (int i = 0; i < 64; ++i) {
;       const unsigned ub = __float_as_uint(rowl[i * 64]);
;       const unsigned o = ub ^ ((unsigned)((int)ub >> 31) | 0x80000000u);
;       x[i] = (i * 64 < nl) ? o : 0u;
;     }
;     unsigned tau = 0u;
;     int cge = 0;
;     switch ((nreg + 7) >> 3) {
.LBB0_2934:
	v_lshlrev_b32_e32 v16, 14, v206
	v_lshlrev_b32_e32 v115, 2, v114
	v_add3_u32 v16, 0, v16, v115
	ds_read2st64_b32 v[164:165], v16 offset1:1
	ds_read2st64_b32 v[166:167], v16 offset0:2 offset1:3
	ds_read2st64_b32 v[168:169], v16 offset0:4 offset1:5
	ds_read2st64_b32 v[170:171], v16 offset0:6 offset1:7
	v_sub_u32_e32 v240, s57, v114
	v_cmp_lt_i32_e32 vcc, s33, v240
	s_movk_i32 s0, 0x140
	s_waitcnt lgkmcnt(3)
	v_ashrrev_i32_e32 v115, 31, v164
	v_bitop3_b32 v239, v115, v164, s58 bitop3:0x36
	v_ashrrev_i32_e32 v115, 31, v165
	v_bitop3_b32 v238, v115, v165, s58 bitop3:0x36
	s_waitcnt lgkmcnt(2)
	v_ashrrev_i32_e32 v115, 31, v166
	v_bitop3_b32 v237, v115, v166, s58 bitop3:0x36
	v_ashrrev_i32_e32 v115, 31, v167
	v_bitop3_b32 v236, v115, v167, s58 bitop3:0x36
	s_waitcnt lgkmcnt(1)
	v_ashrrev_i32_e32 v115, 31, v168
	v_bitop3_b32 v115, v115, v168, s58 bitop3:0x36
	v_cndmask_b32_e32 v235, 0, v115, vcc
	v_ashrrev_i32_e32 v115, 31, v169
	v_bitop3_b32 v115, v115, v169, s58 bitop3:0x36
	v_cmp_lt_i32_e32 vcc, s0, v240
	ds_read2st64_b32 v[164:165], v16 offset0:8 offset1:9
	s_movk_i32 s0, 0x180
	v_cndmask_b32_e32 v234, 0, v115, vcc
	s_waitcnt lgkmcnt(1)
	v_ashrrev_i32_e32 v115, 31, v170
	v_bitop3_b32 v115, v115, v170, s58 bitop3:0x36
	v_cmp_lt_i32_e32 vcc, s0, v240
	s_movk_i32 s0, 0x1c0
	s_add_i32 s38, s57, 63
	v_cndmask_b32_e32 v233, 0, v115, vcc
	v_ashrrev_i32_e32 v115, 31, v171
	v_bitop3_b32 v115, v115, v171, s58 bitop3:0x36
	v_cmp_lt_i32_e32 vcc, s0, v240
	s_movk_i32 s0, 0x200
	ds_read2st64_b32 v[166:167], v16 offset0:10 offset1:11
	ds_read2st64_b32 v[168:169], v16 offset0:12 offset1:13
	ds_read2st64_b32 v[170:171], v16 offset0:14 offset1:15
	v_cndmask_b32_e32 v231, 0, v115, vcc
	s_waitcnt lgkmcnt(3)
	v_ashrrev_i32_e32 v115, 31, v164
	v_bitop3_b32 v115, v115, v164, s58 bitop3:0x36
	v_cmp_lt_i32_e32 vcc, s0, v240
	s_movk_i32 s0, 0x240
	s_lshr_b32 s38, s38, 6
	v_cndmask_b32_e32 v232, 0, v115, vcc
	v_ashrrev_i32_e32 v115, 31, v165
	v_bitop3_b32 v115, v115, v165, s58 bitop3:0x36
	v_cmp_lt_i32_e32 vcc, s0, v240
	s_movk_i32 s0, 0x280
	ds_read2st64_b32 v[164:165], v16 offset0:16 offset1:17
	v_cndmask_b32_e32 v230, 0, v115, vcc
	s_waitcnt lgkmcnt(3)
	v_ashrrev_i32_e32 v115, 31, v166
	v_bitop3_b32 v115, v115, v166, s58 bitop3:0x36
	v_cmp_lt_i32_e32 vcc, s0, v240
	s_movk_i32 s0, 0x2c0
	s_movk_i32 s10, 0xf80
	v_cndmask_b32_e32 v229, 0, v115, vcc
	v_ashrrev_i32_e32 v115, 31, v167
	v_bitop3_b32 v115, v115, v167, s58 bitop3:0x36
	v_cmp_lt_i32_e32 vcc, s0, v240
	s_movk_i32 s0, 0x300
	s_add_i32 s38, s38, 7
	v_cndmask_b32_e32 v228, 0, v115, vcc
	s_waitcnt lgkmcnt(2)
	v_ashrrev_i32_e32 v115, 31, v168
	v_bitop3_b32 v115, v115, v168, s58 bitop3:0x36
	v_cmp_lt_i32_e32 vcc, s0, v240
	s_movk_i32 s0, 0x340
	v_cmp_lt_i32_e64 s[14:15], s10, v240
	v_cndmask_b32_e32 v227, 0, v115, vcc
	v_ashrrev_i32_e32 v115, 31, v169
	v_bitop3_b32 v115, v115, v169, s58 bitop3:0x36
	v_cmp_lt_i32_e32 vcc, s0, v240
	s_movk_i32 s0, 0x380
	s_movk_i32 s10, 0xfc0
	v_cndmask_b32_e32 v226, 0, v115, vcc
	s_waitcnt lgkmcnt(1)
	v_ashrrev_i32_e32 v115, 31, v170
	v_bitop3_b32 v115, v115, v170, s58 bitop3:0x36
	v_cmp_lt_i32_e32 vcc, s0, v240
	s_movk_i32 s0, 0x3c0
	s_lshr_b32 s61, s38, 3
	v_cndmask_b32_e32 v225, 0, v115, vcc
	v_ashrrev_i32_e32 v115, 31, v171
	v_bitop3_b32 v115, v115, v171, s58 bitop3:0x36
	v_cmp_lt_i32_e32 vcc, s0, v240
	s_movk_i32 s0, 0x400
	ds_read2st64_b32 v[166:167], v16 offset0:18 offset1:19
	ds_read2st64_b32 v[168:169], v16 offset0:20 offset1:21
	ds_read2st64_b32 v[170:171], v16 offset0:22 offset1:23
	v_cndmask_b32_e32 v223, 0, v115, vcc
	s_waitcnt lgkmcnt(3)
	v_ashrrev_i32_e32 v115, 31, v164
	v_bitop3_b32 v115, v115, v164, s58 bitop3:0x36
	v_cmp_lt_i32_e32 vcc, s0, v240
	s_movk_i32 s0, 0x440
	v_cmp_lt_i32_e64 s[10:11], s10, v240
	v_cndmask_b32_e32 v224, 0, v115, vcc
	v_ashrrev_i32_e32 v115, 31, v165
	v_bitop3_b32 v115, v115, v165, s58 bitop3:0x36
	v_cmp_lt_i32_e32 vcc, s0, v240
	s_movk_i32 s0, 0x480
	ds_read2st64_b32 v[164:165], v16 offset0:24 offset1:25
	v_cndmask_b32_e32 v222, 0, v115, vcc
	s_waitcnt lgkmcnt(3)
	v_ashrrev_i32_e32 v115, 31, v166
	v_bitop3_b32 v115, v115, v166, s58 bitop3:0x36
	v_cmp_lt_i32_e32 vcc, s0, v240
	s_movk_i32 s0, 0x4c0
	s_cmp_lt_i32 s61, 4
	v_cndmask_b32_e32 v221, 0, v115, vcc
	v_ashrrev_i32_e32 v115, 31, v167
	v_bitop3_b32 v115, v115, v167, s58 bitop3:0x36
	v_cmp_lt_i32_e32 vcc, s0, v240
	s_movk_i32 s0, 0x500
	s_mov_b64 s[40:41], 0
	v_cndmask_b32_e32 v220, 0, v115, vcc
	s_waitcnt lgkmcnt(2)
	v_ashrrev_i32_e32 v115, 31, v168
	v_bitop3_b32 v115, v115, v168, s58 bitop3:0x36
	v_cmp_lt_i32_e32 vcc, s0, v240
	s_movk_i32 s0, 0x540
	s_nop 0
	v_cndmask_b32_e32 v219, 0, v115, vcc
	v_ashrrev_i32_e32 v115, 31, v169
	v_bitop3_b32 v115, v115, v169, s58 bitop3:0x36
	v_cmp_lt_i32_e32 vcc, s0, v240
	s_movk_i32 s0, 0x580
	s_nop 0
	v_cndmask_b32_e32 v218, 0, v115, vcc
	s_waitcnt lgkmcnt(1)
	v_ashrrev_i32_e32 v115, 31, v170
	v_bitop3_b32 v115, v115, v170, s58 bitop3:0x36
	v_cmp_lt_i32_e32 vcc, s0, v240
	s_movk_i32 s0, 0x5c0
	s_nop 0
	v_cndmask_b32_e32 v217, 0, v115, vcc
	v_ashrrev_i32_e32 v115, 31, v171
	v_bitop3_b32 v115, v115, v171, s58 bitop3:0x36
	v_cmp_lt_i32_e32 vcc, s0, v240
	s_movk_i32 s0, 0x600
	ds_read2st64_b32 v[166:167], v16 offset0:26 offset1:27
	ds_read2st64_b32 v[168:169], v16 offset0:28 offset1:29
	ds_read2st64_b32 v[170:171], v16 offset0:30 offset1:31
	v_cndmask_b32_e32 v215, 0, v115, vcc
	s_waitcnt lgkmcnt(3)
	v_ashrrev_i32_e32 v115, 31, v164
	v_bitop3_b32 v115, v115, v164, s58 bitop3:0x36
	v_cmp_lt_i32_e32 vcc, s0, v240
	s_movk_i32 s0, 0x640
	s_nop 0
	v_cndmask_b32_e32 v216, 0, v115, vcc
	v_ashrrev_i32_e32 v115, 31, v165
	v_bitop3_b32 v115, v115, v165, s58 bitop3:0x36
	v_cmp_lt_i32_e32 vcc, s0, v240
	s_movk_i32 s0, 0x680
	ds_read2st64_b32 v[164:165], v16 offset0:32 offset1:33
	v_cndmask_b32_e32 v214, 0, v115, vcc
	s_waitcnt lgkmcnt(3)
; __device__ __forceinline__ void select_group(unsigned char* ws, int r0, const bf16_t* __restrict__ kib, int n, float* sc, SelPre& pre, int nr0, const bf16_t* __restrict__ nkib, int nn) {
;     ...
; #pragma unroll
;     for (int i = 0; i < 64; ++i) {
;       const unsigned ub = __float_as_uint(rowl[i * 64]);
;       const unsigned o = ub ^ ((unsigned)((int)ub >> 31) | 0x80000000u);
;       x[i] = (i * 64 < nl) ? o : 0u;
;     }
;     unsigned tau = 0u;
;     int cge = 0;
;     switch ((nreg + 7) >> 3) {
	v_ashrrev_i32_e32 v115, 31, v166
	v_bitop3_b32 v115, v115, v166, s58 bitop3:0x36
	v_cmp_lt_i32_e32 vcc, s0, v240
	s_movk_i32 s0, 0x6c0
	s_nop 0
	v_cndmask_b32_e32 v213, 0, v115, vcc
	v_ashrrev_i32_e32 v115, 31, v167
	v_bitop3_b32 v115, v115, v167, s58 bitop3:0x36
	v_cmp_lt_i32_e32 vcc, s0, v240
	s_movk_i32 s0, 0x700
	s_nop 0
	v_cndmask_b32_e32 v212, 0, v115, vcc
	s_waitcnt lgkmcnt(2)
	v_ashrrev_i32_e32 v115, 31, v168
	v_bitop3_b32 v115, v115, v168, s58 bitop3:0x36
	v_cmp_lt_i32_e32 vcc, s0, v240
	s_movk_i32 s0, 0x740
	s_nop 0
	v_cndmask_b32_e32 v211, 0, v115, vcc
	v_ashrrev_i32_e32 v115, 31, v169
	v_bitop3_b32 v115, v115, v169, s58 bitop3:0x36
	v_cmp_lt_i32_e32 vcc, s0, v240
	s_movk_i32 s0, 0x780
	s_nop 0
	v_cndmask_b32_e32 v210, 0, v115, vcc
	s_waitcnt lgkmcnt(1)
	v_ashrrev_i32_e32 v115, 31, v170
	v_bitop3_b32 v115, v115, v170, s58 bitop3:0x36
	v_cmp_lt_i32_e32 vcc, s0, v240
	s_movk_i32 s0, 0x7c0
	s_nop 0
	v_cndmask_b32_e32 v207, 0, v115, vcc
	v_ashrrev_i32_e32 v115, 31, v171
	v_bitop3_b32 v115, v115, v171, s58 bitop3:0x36
	v_cmp_lt_i32_e32 vcc, s0, v240
	s_movk_i32 s0, 0x800
	ds_read2st64_b32 v[166:167], v16 offset0:34 offset1:35
	ds_read2st64_b32 v[168:169], v16 offset0:36 offset1:37
	ds_read2st64_b32 v[170:171], v16 offset0:38 offset1:39
	v_cndmask_b32_e32 v194, 0, v115, vcc
	s_waitcnt lgkmcnt(3)
	v_ashrrev_i32_e32 v115, 31, v164
	v_bitop3_b32 v115, v115, v164, s58 bitop3:0x36
	v_cmp_lt_i32_e32 vcc, s0, v240
	s_movk_i32 s0, 0x840
	s_nop 0
	v_cndmask_b32_e32 v195, 0, v115, vcc
	v_ashrrev_i32_e32 v115, 31, v165
	v_bitop3_b32 v115, v115, v165, s58 bitop3:0x36
	v_cmp_lt_i32_e32 vcc, s0, v240
	s_movk_i32 s0, 0x880
	ds_read2st64_b32 v[164:165], v16 offset0:40 offset1:41
	v_cndmask_b32_e32 v193, 0, v115, vcc
	s_waitcnt lgkmcnt(3)
	v_ashrrev_i32_e32 v115, 31, v166
	v_bitop3_b32 v115, v115, v166, s58 bitop3:0x36
	v_cmp_lt_i32_e32 vcc, s0, v240
	s_movk_i32 s0, 0x8c0
	s_nop 0
	v_cndmask_b32_e32 v192, 0, v115, vcc
	v_ashrrev_i32_e32 v115, 31, v167
	v_bitop3_b32 v115, v115, v167, s58 bitop3:0x36
	v_cmp_lt_i32_e32 vcc, s0, v240
	s_movk_i32 s0, 0x900
	s_nop 0
	v_cndmask_b32_e32 v191, 0, v115, vcc
	s_waitcnt lgkmcnt(2)
	v_ashrrev_i32_e32 v115, 31, v168
	v_bitop3_b32 v115, v115, v168, s58 bitop3:0x36
	v_cmp_lt_i32_e32 vcc, s0, v240
	s_movk_i32 s0, 0x940
	s_nop 0
	v_cndmask_b32_e32 v190, 0, v115, vcc
	v_ashrrev_i32_e32 v115, 31, v169
	v_bitop3_b32 v115, v115, v169, s58 bitop3:0x36
	v_cmp_lt_i32_e32 vcc, s0, v240
	s_movk_i32 s0, 0x980
	s_nop 0
	v_cndmask_b32_e32 v189, 0, v115, vcc
	s_waitcnt lgkmcnt(1)
	v_ashrrev_i32_e32 v115, 31, v170
	v_bitop3_b32 v115, v115, v170, s58 bitop3:0x36
	v_cmp_lt_i32_e32 vcc, s0, v240
	s_movk_i32 s0, 0x9c0
	s_nop 0
	v_cndmask_b32_e32 v188, 0, v115, vcc
	v_ashrrev_i32_e32 v115, 31, v171
	v_bitop3_b32 v115, v115, v171, s58 bitop3:0x36
	v_cmp_lt_i32_e32 vcc, s0, v240
	s_movk_i32 s0, 0xa00
	ds_read2st64_b32 v[166:167], v16 offset0:42 offset1:43
	ds_read2st64_b32 v[168:169], v16 offset0:44 offset1:45
	ds_read2st64_b32 v[170:171], v16 offset0:46 offset1:47
	v_cndmask_b32_e32 v186, 0, v115, vcc
	s_waitcnt lgkmcnt(3)
	v_ashrrev_i32_e32 v115, 31, v164
	v_bitop3_b32 v115, v115, v164, s58 bitop3:0x36
	v_cmp_lt_i32_e32 vcc, s0, v240
	s_movk_i32 s0, 0xa40
	s_nop 0
	v_cndmask_b32_e32 v187, 0, v115, vcc
	v_ashrrev_i32_e32 v115, 31, v165
	v_bitop3_b32 v115, v115, v165, s58 bitop3:0x36
	v_cmp_lt_i32_e32 vcc, s0, v240
	s_movk_i32 s0, 0xa80
	ds_read2st64_b32 v[164:165], v16 offset0:48 offset1:49
	v_cndmask_b32_e32 v185, 0, v115, vcc
	s_waitcnt lgkmcnt(3)
	v_ashrrev_i32_e32 v115, 31, v166
	v_bitop3_b32 v115, v115, v166, s58 bitop3:0x36
	v_cmp_lt_i32_e32 vcc, s0, v240
	s_movk_i32 s0, 0xac0
	s_nop 0
	v_cndmask_b32_e32 v184, 0, v115, vcc
	v_ashrrev_i32_e32 v115, 31, v167
	v_bitop3_b32 v115, v115, v167, s58 bitop3:0x36
	v_cmp_lt_i32_e32 vcc, s0, v240
	s_movk_i32 s0, 0xb00
	s_nop 0
	v_cndmask_b32_e32 v183, 0, v115, vcc
	s_waitcnt lgkmcnt(2)
	v_ashrrev_i32_e32 v115, 31, v168
	v_bitop3_b32 v115, v115, v168, s58 bitop3:0x36
	v_cmp_lt_i32_e32 vcc, s0, v240
	s_movk_i32 s0, 0xb40
	s_nop 0
	v_cndmask_b32_e32 v182, 0, v115, vcc
	v_ashrrev_i32_e32 v115, 31, v169
	v_bitop3_b32 v115, v115, v169, s58 bitop3:0x36
	v_cmp_lt_i32_e32 vcc, s0, v240
	s_movk_i32 s0, 0xb80
	s_nop 0
	v_cndmask_b32_e32 v181, 0, v115, vcc
	s_waitcnt lgkmcnt(1)
	v_ashrrev_i32_e32 v115, 31, v170
	v_bitop3_b32 v115, v115, v170, s58 bitop3:0x36
	v_cmp_lt_i32_e32 vcc, s0, v240
	s_movk_i32 s0, 0xbc0
	s_nop 0
	v_cndmask_b32_e32 v180, 0, v115, vcc
	v_ashrrev_i32_e32 v115, 31, v171
	v_bitop3_b32 v115, v115, v171, s58 bitop3:0x36
	v_cmp_lt_i32_e32 vcc, s0, v240
	s_movk_i32 s0, 0xc00
	ds_read2st64_b32 v[166:167], v16 offset0:50 offset1:51
	ds_read2st64_b32 v[168:169], v16 offset0:52 offset1:53
	ds_read2st64_b32 v[170:171], v16 offset0:54 offset1:55
	v_cndmask_b32_e32 v178, 0, v115, vcc
	s_waitcnt lgkmcnt(3)
	v_ashrrev_i32_e32 v115, 31, v164
	v_bitop3_b32 v115, v115, v164, s58 bitop3:0x36
	v_cmp_lt_i32_e32 vcc, s0, v240
	s_movk_i32 s0, 0xc40
	s_nop 0
	v_cndmask_b32_e32 v179, 0, v115, vcc
	v_ashrrev_i32_e32 v115, 31, v165
	v_bitop3_b32 v115, v115, v165, s58 bitop3:0x36
	v_cmp_lt_i32_e32 vcc, s0, v240
	s_movk_i32 s0, 0xc80
	s_nop 0
	v_cndmask_b32_e32 v177, 0, v115, vcc
	s_waitcnt lgkmcnt(2)
	v_ashrrev_i32_e32 v115, 31, v166
	v_bitop3_b32 v115, v115, v166, s58 bitop3:0x36
	v_cmp_lt_i32_e32 vcc, s0, v240
	s_movk_i32 s0, 0xcc0
	s_nop 0
	v_cndmask_b32_e32 v176, 0, v115, vcc
	v_ashrrev_i32_e32 v115, 31, v167
	v_bitop3_b32 v115, v115, v167, s58 bitop3:0x36
	v_cmp_lt_i32_e32 vcc, s0, v240
	s_movk_i32 s0, 0xd00
	s_nop 0
	v_cndmask_b32_e32 v175, 0, v115, vcc
	s_waitcnt lgkmcnt(1)
	v_ashrrev_i32_e32 v115, 31, v168
	v_bitop3_b32 v115, v115, v168, s58 bitop3:0x36
	v_cmp_lt_i32_e32 vcc, s0, v240
	s_movk_i32 s0, 0xd40
	s_nop 0
	v_cndmask_b32_e32 v174, 0, v115, vcc
	v_ashrrev_i32_e32 v115, 31, v169
	v_bitop3_b32 v115, v115, v169, s58 bitop3:0x36
	v_cmp_lt_i32_e32 vcc, s0, v240
	s_movk_i32 s0, 0xd80
	s_nop 0
	v_cndmask_b32_e32 v173, 0, v115, vcc
	s_waitcnt lgkmcnt(0)
	v_ashrrev_i32_e32 v115, 31, v170
	v_bitop3_b32 v115, v115, v170, s58 bitop3:0x36
	v_cmp_lt_i32_e32 vcc, s0, v240
	s_movk_i32 s0, 0xdc0
	s_nop 0
	v_cndmask_b32_e32 v172, 0, v115, vcc
	v_ashrrev_i32_e32 v115, 31, v171
	v_bitop3_b32 v115, v115, v171, s58 bitop3:0x36
	v_cmp_lt_i32_e32 vcc, s0, v240
	s_movk_i32 s0, 0xe00
	ds_read2st64_b32 v[170:171], v16 offset0:56 offset1:57
	ds_read2st64_b32 v[168:169], v16 offset0:58 offset1:59
	ds_read2st64_b32 v[166:167], v16 offset0:60 offset1:61
	ds_read2st64_b32 v[164:165], v16 offset0:62 offset1:63
	v_cmp_lt_i32_e64 s[12:13], s0, v240
	s_movk_i32 s0, 0xe40
	v_cmp_lt_i32_e64 s[6:7], s0, v240
	s_movk_i32 s0, 0xe80
	v_cmp_lt_i32_e64 s[8:9], s0, v240
	s_movk_i32 s0, 0xec0
	v_cmp_lt_i32_e64 s[2:3], s0, v240
	s_movk_i32 s0, 0xf00
	v_cmp_lt_i32_e64 s[4:5], s0, v240
	s_movk_i32 s0, 0xf40
	v_cndmask_b32_e32 v115, 0, v115, vcc
	v_cmp_lt_i32_e64 s[0:1], s0, v240
	s_cbranch_scc1 .LBB0_2941
; template <int NB>
; __device__ __forceinline__ void bisect256(const unsigned (&x)[64], unsigned& tau_out, int& cge_out) {
;     ...
;     const unsigned cand = tau | (1u << bit);
;     unsigned cl = 0u;
; #pragma unroll
;     for (int blk = 0; blk < NB; ++blk) {
;       unsigned long long m0, m1, m2, m3, m4, m5, m6, m7;
;       asm volatile(
;           "v_cmp_ge_u32_e64 %1, %9, %17\n\tv_cmp_ge_u32_e64 %2, %10, %17\n\tv_cmp_ge_u32_e64 %3, %11, %17\n\tv_cmp_ge_u32_e64 %4, %12, %17\n\t"
;           "v_cmp_ge_u32_e64 %5, %13, %17\n\tv_cmp_ge_u32_e64 %6, %14, %17\n\tv_cmp_ge_u32_e64 %7, %15, %17\n\tv_cmp_ge_u32_e64 %8, %16, %17\n\t"
;           "v_addc_co_u32_e64 %0, %1, 0, %0, %1\n\tv_addc_co_u32_e64 %0, %2, 0, %0, %2\n\tv_addc_co_u32_e64 %0, %3, 0, %0, %3\n\t"
;           "v_addc_co_u32_e64 %0, %4, 0, %0, %4\n\tv_addc_co_u32_e64 %0, %5, 0, %0, %5\n\tv_addc_co_u32_e64 %0, %6, 0, %0, %6\n\t"
;           "v_addc_co_u32_e64 %0, %7, 0, %0, %7\n\tv_addc_co_u32_e64 %0, %8, 0, %0, %8"
;           : "+v"(cl), "=&s"(m0), "=&s"(m1), "=&s"(m2), "=&s"(m3), "=&s"(m4), "=&s"(m5), "=&s"(m6), "=&s"(m7)
;           : "v"(x[blk * 8 + 0]), "v"(x[blk * 8 + 1]), "v"(x[blk * 8 + 2]), "v"(x[blk * 8 + 3]), "v"(x[blk * 8 + 4]), "v"(x[blk * 8 + 5]),
;             "v"(x[blk * 8 + 6]), "v"(x[blk * 8 + 7]), "v"(cand));
;     }
;     cl += (unsigned)__builtin_amdgcn_update_dpp(0, (int)cl, 0x111, 0xf, 0xf, true);
;     cl += (unsigned)__builtin_amdgcn_update_dpp(0, (int)cl, 0x112, 0xf, 0xf, true);
;     cl += (unsigned)__builtin_amdgcn_update_dpp(0, (int)cl, 0x114, 0xf, 0xf, true);
;     cl += (unsigned)__builtin_amdgcn_update_dpp(0, (int)cl, 0x118, 0xf, 0xf, true);
;     const int cnt = __builtin_amdgcn_readlane((int)cl, 15) + __builtin_amdgcn_readlane((int)cl, 31) + __builtin_amdgcn_readlane((int)cl, 47) +
;                     __builtin_amdgcn_readlane((int)cl, 63);
;     if (cnt >= 256) { tau = cand; cge = cnt; }
;     if (cnt == 256) break;
;   }
; __device__ __forceinline__ void select_group(unsigned char* ws, int r0, const bf16_t* __restrict__ kib, int n, float* sc, SelPre& pre, int nr0, const bf16_t* __restrict__ nkib, int nn) {
;     ...
;     switch ((nreg + 7) >> 3) {
;       case 1: bisect256<1>(x, tau, cge); break;
;       case 2: bisect256<2>(x, tau, cge); break;
;       case 3: bisect256<3>(x, tau, cge); break;
;       case 4: bisect256<4>(x, tau, cge); break;
	s_cmp_gt_i32 s61, 5
	s_cbranch_scc0 .LBB0_2942
	s_cmp_gt_i32 s61, 6
	s_cbranch_scc0 .LBB0_2943
	s_cmp_eq_u32 s61, 7
	s_cbranch_scc0 .LBB0_2944
	s_mov_b32 s59, 0
	s_mov_b32 s101, 0
	s_mov_b32 vcc_hi, 0x80000000
.Lselq0_top:
	s_or_b32 vcc_lo, s101, vcc_hi
	v_mov_b32_e32 v242, v17
	v_cmp_ge_u32_e64 s[38:39], v239, vcc_lo
	v_cmp_ge_u32_e64 s[42:43], v238, vcc_lo
	v_cmp_ge_u32_e64 s[62:63], v237, vcc_lo
	v_cmp_ge_u32_e64 s[64:65], v236, vcc_lo
	v_cmp_ge_u32_e64 s[66:67], v235, vcc_lo
	v_cmp_ge_u32_e64 s[68:69], v234, vcc_lo
	v_cmp_ge_u32_e64 s[70:71], v233, vcc_lo
	v_cmp_ge_u32_e64 s[72:73], v231, vcc_lo
	v_addc_co_u32_e64 v242, s[38:39], 0, v242, s[38:39]
	v_addc_co_u32_e64 v242, s[42:43], 0, v242, s[42:43]
	v_addc_co_u32_e64 v242, s[62:63], 0, v242, s[62:63]
	v_addc_co_u32_e64 v242, s[64:65], 0, v242, s[64:65]
	v_addc_co_u32_e64 v242, s[66:67], 0, v242, s[66:67]
	v_addc_co_u32_e64 v242, s[68:69], 0, v242, s[68:69]
	v_addc_co_u32_e64 v242, s[70:71], 0, v242, s[70:71]
	v_addc_co_u32_e64 v242, s[72:73], 0, v242, s[72:73]
	v_cmp_ge_u32_e64 s[38:39], v232, vcc_lo
	v_cmp_ge_u32_e64 s[42:43], v230, vcc_lo
	v_cmp_ge_u32_e64 s[62:63], v229, vcc_lo
	v_cmp_ge_u32_e64 s[64:65], v228, vcc_lo
	v_cmp_ge_u32_e64 s[66:67], v227, vcc_lo
	v_cmp_ge_u32_e64 s[68:69], v226, vcc_lo
	v_cmp_ge_u32_e64 s[70:71], v225, vcc_lo
	v_cmp_ge_u32_e64 s[72:73], v223, vcc_lo
	v_addc_co_u32_e64 v242, s[38:39], 0, v242, s[38:39]
	v_addc_co_u32_e64 v242, s[42:43], 0, v242, s[42:43]
	v_addc_co_u32_e64 v242, s[62:63], 0, v242, s[62:63]
	v_addc_co_u32_e64 v242, s[64:65], 0, v242, s[64:65]
	v_addc_co_u32_e64 v242, s[66:67], 0, v242, s[66:67]
	v_addc_co_u32_e64 v242, s[68:69], 0, v242, s[68:69]
	v_addc_co_u32_e64 v242, s[70:71], 0, v242, s[70:71]
	v_addc_co_u32_e64 v242, s[72:73], 0, v242, s[72:73]
	v_cmp_ge_u32_e64 s[38:39], v224, vcc_lo
	v_cmp_ge_u32_e64 s[42:43], v222, vcc_lo
	v_cmp_ge_u32_e64 s[62:63], v221, vcc_lo
	v_cmp_ge_u32_e64 s[64:65], v220, vcc_lo
	v_cmp_ge_u32_e64 s[66:67], v219, vcc_lo
	v_cmp_ge_u32_e64 s[68:69], v218, vcc_lo
	v_cmp_ge_u32_e64 s[70:71], v217, vcc_lo
	v_cmp_ge_u32_e64 s[72:73], v215, vcc_lo
	v_addc_co_u32_e64 v242, s[38:39], 0, v242, s[38:39]
	v_addc_co_u32_e64 v242, s[42:43], 0, v242, s[42:43]
	v_addc_co_u32_e64 v242, s[62:63], 0, v242, s[62:63]
	v_addc_co_u32_e64 v242, s[64:65], 0, v242, s[64:65]
	v_addc_co_u32_e64 v242, s[66:67], 0, v242, s[66:67]
	v_addc_co_u32_e64 v242, s[68:69], 0, v242, s[68:69]
	v_addc_co_u32_e64 v242, s[70:71], 0, v242, s[70:71]
	v_addc_co_u32_e64 v242, s[72:73], 0, v242, s[72:73]
	v_cmp_ge_u32_e64 s[38:39], v216, vcc_lo
	v_cmp_ge_u32_e64 s[42:43], v214, vcc_lo
	v_cmp_ge_u32_e64 s[62:63], v213, vcc_lo
	v_cmp_ge_u32_e64 s[64:65], v212, vcc_lo
	v_cmp_ge_u32_e64 s[66:67], v211, vcc_lo
	v_cmp_ge_u32_e64 s[68:69], v210, vcc_lo
	v_cmp_ge_u32_e64 s[70:71], v207, vcc_lo
	v_cmp_ge_u32_e64 s[72:73], v194, vcc_lo
	v_addc_co_u32_e64 v242, s[38:39], 0, v242, s[38:39]
	v_addc_co_u32_e64 v242, s[42:43], 0, v242, s[42:43]
	v_addc_co_u32_e64 v242, s[62:63], 0, v242, s[62:63]
	v_addc_co_u32_e64 v242, s[64:65], 0, v242, s[64:65]
	v_addc_co_u32_e64 v242, s[66:67], 0, v242, s[66:67]
	v_addc_co_u32_e64 v242, s[68:69], 0, v242, s[68:69]
	v_addc_co_u32_e64 v242, s[70:71], 0, v242, s[70:71]
	v_addc_co_u32_e64 v242, s[72:73], 0, v242, s[72:73]
	v_cmp_ge_u32_e64 s[38:39], v195, vcc_lo
	v_cmp_ge_u32_e64 s[42:43], v193, vcc_lo
	v_cmp_ge_u32_e64 s[62:63], v192, vcc_lo
	v_cmp_ge_u32_e64 s[64:65], v191, vcc_lo
	v_cmp_ge_u32_e64 s[66:67], v190, vcc_lo
	v_cmp_ge_u32_e64 s[68:69], v189, vcc_lo
	v_cmp_ge_u32_e64 s[70:71], v188, vcc_lo
	v_cmp_ge_u32_e64 s[72:73], v186, vcc_lo
	v_addc_co_u32_e64 v242, s[38:39], 0, v242, s[38:39]
	v_addc_co_u32_e64 v242, s[42:43], 0, v242, s[42:43]
	v_addc_co_u32_e64 v242, s[62:63], 0, v242, s[62:63]
	v_addc_co_u32_e64 v242, s[64:65], 0, v242, s[64:65]
	v_addc_co_u32_e64 v242, s[66:67], 0, v242, s[66:67]
	v_addc_co_u32_e64 v242, s[68:69], 0, v242, s[68:69]
	v_addc_co_u32_e64 v242, s[70:71], 0, v242, s[70:71]
	v_addc_co_u32_e64 v242, s[72:73], 0, v242, s[72:73]
	v_cmp_ge_u32_e64 s[38:39], v187, vcc_lo
	v_cmp_ge_u32_e64 s[42:43], v185, vcc_lo
	v_cmp_ge_u32_e64 s[62:63], v184, vcc_lo
	v_cmp_ge_u32_e64 s[64:65], v183, vcc_lo
	v_cmp_ge_u32_e64 s[66:67], v182, vcc_lo
	v_cmp_ge_u32_e64 s[68:69], v181, vcc_lo
	v_cmp_ge_u32_e64 s[70:71], v180, vcc_lo
	v_cmp_ge_u32_e64 s[72:73], v178, vcc_lo
	v_addc_co_u32_e64 v242, s[38:39], 0, v242, s[38:39]
	v_addc_co_u32_e64 v242, s[42:43], 0, v242, s[42:43]
	v_addc_co_u32_e64 v242, s[62:63], 0, v242, s[62:63]
	v_addc_co_u32_e64 v242, s[64:65], 0, v242, s[64:65]
	v_addc_co_u32_e64 v242, s[66:67], 0, v242, s[66:67]
	v_addc_co_u32_e64 v242, s[68:69], 0, v242, s[68:69]
	v_addc_co_u32_e64 v242, s[70:71], 0, v242, s[70:71]
	v_addc_co_u32_e64 v242, s[72:73], 0, v242, s[72:73]
	v_cmp_ge_u32_e64 s[38:39], v179, vcc_lo
	v_cmp_ge_u32_e64 s[42:43], v177, vcc_lo
	v_cmp_ge_u32_e64 s[62:63], v176, vcc_lo
	v_cmp_ge_u32_e64 s[64:65], v175, vcc_lo
	v_cmp_ge_u32_e64 s[66:67], v174, vcc_lo
	v_cmp_ge_u32_e64 s[68:69], v173, vcc_lo
	v_cmp_ge_u32_e64 s[70:71], v172, vcc_lo
	v_cmp_ge_u32_e64 s[72:73], v115, vcc_lo
	v_addc_co_u32_e64 v242, s[38:39], 0, v242, s[38:39]
	v_addc_co_u32_e64 v242, s[42:43], 0, v242, s[42:43]
	v_addc_co_u32_e64 v242, s[62:63], 0, v242, s[62:63]
	v_addc_co_u32_e64 v242, s[64:65], 0, v242, s[64:65]
	v_addc_co_u32_e64 v242, s[66:67], 0, v242, s[66:67]
	v_addc_co_u32_e64 v242, s[68:69], 0, v242, s[68:69]
	v_addc_co_u32_e64 v242, s[70:71], 0, v242, s[70:71]
	v_addc_co_u32_e64 v242, s[72:73], 0, v242, s[72:73]
	s_nop 1
	v_add_u32_dpp v242, v242, v242 row_shr:1 row_mask:0xf bank_mask:0xf bound_ctrl:1
	s_nop 1
	v_add_u32_dpp v242, v242, v242 row_shr:2 row_mask:0xf bank_mask:0xf bound_ctrl:1
	s_nop 1
	v_add_u32_dpp v242, v242, v242 row_shr:4 row_mask:0xf bank_mask:0xf bound_ctrl:1
	s_nop 1
	v_add_u32_dpp v242, v242, v242 row_shr:8 row_mask:0xf bank_mask:0xf bound_ctrl:1
	s_nop 0
	v_readlane_b32 s38, v242, 15
	v_readlane_b32 s39, v242, 31
	s_add_i32 s38, s39, s38
	v_readlane_b32 s39, v242, 47
	s_add_i32 s38, s38, s39
	v_readlane_b32 s39, v242, 63
	s_add_i32 s38, s38, s39
	s_cmpk_gt_i32 s38, 0xff
	s_cselect_b32 s59, s38, s59
	s_cselect_b32 s101, vcc_lo, s101
	s_cmpk_eq_i32 s38, 0x100
	s_cbranch_scc1 .Lselq0_exit
	s_lshr_b32 vcc_hi, vcc_hi, 1
	s_cmp_lg_u32 vcc_hi, 0
	s_cbranch_scc1 .Lselq0_top

; template <int NB>
; __device__ __forceinline__ void bisect256(const unsigned (&x)[64], unsigned& tau_out, int& cge_out) {
;     ...
;     const unsigned cand = tau | (1u << bit);
;     unsigned cl = 0u;
; #pragma unroll
;     for (int blk = 0; blk < NB; ++blk) {
;       unsigned long long m0, m1, m2, m3, m4, m5, m6, m7;
;       asm volatile(
;           "v_cmp_ge_u32_e64 %1, %9, %17\n\tv_cmp_ge_u32_e64 %2, %10, %17\n\tv_cmp_ge_u32_e64 %3, %11, %17\n\tv_cmp_ge_u32_e64 %4, %12, %17\n\t"
;           "v_cmp_ge_u32_e64 %5, %13, %17\n\tv_cmp_ge_u32_e64 %6, %14, %17\n\tv_cmp_ge_u32_e64 %7, %15, %17\n\tv_cmp_ge_u32_e64 %8, %16, %17\n\t"
;           "v_addc_co_u32_e64 %0, %1, 0, %0, %1\n\tv_addc_co_u32_e64 %0, %2, 0, %0, %2\n\tv_addc_co_u32_e64 %0, %3, 0, %0, %3\n\t"
;           "v_addc_co_u32_e64 %0, %4, 0, %0, %4\n\tv_addc_co_u32_e64 %0, %5, 0, %0, %5\n\tv_addc_co_u32_e64 %0, %6, 0, %0, %6\n\t"
;           "v_addc_co_u32_e64 %0, %7, 0, %0, %7\n\tv_addc_co_u32_e64 %0, %8, 0, %0, %8"
;           : "+v"(cl), "=&s"(m0), "=&s"(m1), "=&s"(m2), "=&s"(m3), "=&s"(m4), "=&s"(m5), "=&s"(m6), "=&s"(m7)
;           : "v"(x[blk * 8 + 0]), "v"(x[blk * 8 + 1]), "v"(x[blk * 8 + 2]), "v"(x[blk * 8 + 3]), "v"(x[blk * 8 + 4]), "v"(x[blk * 8 + 5]),
;             "v"(x[blk * 8 + 6]), "v"(x[blk * 8 + 7]), "v"(cand));
;     }
;     cl += (unsigned)__builtin_amdgcn_update_dpp(0, (int)cl, 0x111, 0xf, 0xf, true);
;     cl += (unsigned)__builtin_amdgcn_update_dpp(0, (int)cl, 0x112, 0xf, 0xf, true);
;     cl += (unsigned)__builtin_amdgcn_update_dpp(0, (int)cl, 0x114, 0xf, 0xf, true);
;     cl += (unsigned)__builtin_amdgcn_update_dpp(0, (int)cl, 0x118, 0xf, 0xf, true);
;     const int cnt = __builtin_amdgcn_readlane((int)cl, 15) + __builtin_amdgcn_readlane((int)cl, 31) + __builtin_amdgcn_readlane((int)cl, 47) +
;                     __builtin_amdgcn_readlane((int)cl, 63);
;     if (cnt >= 256) { tau = cand; cge = cnt; }
;     if (cnt == 256) break;
;   }
.LBB0_2945:
	s_mov_b32 s59, 0
	s_mov_b32 s101, 0
	s_mov_b32 vcc_hi, 0x80000000
.Lselq1_top:
	s_or_b32 vcc_lo, s101, vcc_hi
	v_mov_b32_e32 v242, v17
	v_cmp_ge_u32_e64 s[42:43], v239, vcc_lo
	v_cmp_ge_u32_e64 s[62:63], v238, vcc_lo
	v_cmp_ge_u32_e64 s[64:65], v237, vcc_lo
	v_cmp_ge_u32_e64 s[66:67], v236, vcc_lo
	v_cmp_ge_u32_e64 s[68:69], v235, vcc_lo
	v_cmp_ge_u32_e64 s[70:71], v234, vcc_lo
	v_cmp_ge_u32_e64 s[72:73], v233, vcc_lo
	v_cmp_ge_u32_e64 s[74:75], v231, vcc_lo
	v_addc_co_u32_e64 v242, s[42:43], 0, v242, s[42:43]
	v_addc_co_u32_e64 v242, s[62:63], 0, v242, s[62:63]
	v_addc_co_u32_e64 v242, s[64:65], 0, v242, s[64:65]
	v_addc_co_u32_e64 v242, s[66:67], 0, v242, s[66:67]
	v_addc_co_u32_e64 v242, s[68:69], 0, v242, s[68:69]
	v_addc_co_u32_e64 v242, s[70:71], 0, v242, s[70:71]
	v_addc_co_u32_e64 v242, s[72:73], 0, v242, s[72:73]
	v_addc_co_u32_e64 v242, s[74:75], 0, v242, s[74:75]
	v_cmp_ge_u32_e64 s[42:43], v232, vcc_lo
	v_cmp_ge_u32_e64 s[62:63], v230, vcc_lo
	v_cmp_ge_u32_e64 s[64:65], v229, vcc_lo
	v_cmp_ge_u32_e64 s[66:67], v228, vcc_lo
	v_cmp_ge_u32_e64 s[68:69], v227, vcc_lo
	v_cmp_ge_u32_e64 s[70:71], v226, vcc_lo
	v_cmp_ge_u32_e64 s[72:73], v225, vcc_lo
	v_cmp_ge_u32_e64 s[74:75], v223, vcc_lo
	v_addc_co_u32_e64 v242, s[42:43], 0, v242, s[42:43]
	v_addc_co_u32_e64 v242, s[62:63], 0, v242, s[62:63]
	v_addc_co_u32_e64 v242, s[64:65], 0, v242, s[64:65]
	v_addc_co_u32_e64 v242, s[66:67], 0, v242, s[66:67]
	v_addc_co_u32_e64 v242, s[68:69], 0, v242, s[68:69]
	v_addc_co_u32_e64 v242, s[70:71], 0, v242, s[70:71]
	v_addc_co_u32_e64 v242, s[72:73], 0, v242, s[72:73]
	v_addc_co_u32_e64 v242, s[74:75], 0, v242, s[74:75]
	v_cmp_ge_u32_e64 s[42:43], v224, vcc_lo
	v_cmp_ge_u32_e64 s[62:63], v222, vcc_lo
	v_cmp_ge_u32_e64 s[64:65], v221, vcc_lo
	v_cmp_ge_u32_e64 s[66:67], v220, vcc_lo
	v_cmp_ge_u32_e64 s[68:69], v219, vcc_lo
	v_cmp_ge_u32_e64 s[70:71], v218, vcc_lo
	v_cmp_ge_u32_e64 s[72:73], v217, vcc_lo
	v_cmp_ge_u32_e64 s[74:75], v215, vcc_lo
	v_addc_co_u32_e64 v242, s[42:43], 0, v242, s[42:43]
	v_addc_co_u32_e64 v242, s[62:63], 0, v242, s[62:63]
	v_addc_co_u32_e64 v242, s[64:65], 0, v242, s[64:65]
	v_addc_co_u32_e64 v242, s[66:67], 0, v242, s[66:67]
	v_addc_co_u32_e64 v242, s[68:69], 0, v242, s[68:69]
	v_addc_co_u32_e64 v242, s[70:71], 0, v242, s[70:71]
	v_addc_co_u32_e64 v242, s[72:73], 0, v242, s[72:73]
	v_addc_co_u32_e64 v242, s[74:75], 0, v242, s[74:75]
	v_cmp_ge_u32_e64 s[42:43], v216, vcc_lo
	v_cmp_ge_u32_e64 s[62:63], v214, vcc_lo
	v_cmp_ge_u32_e64 s[64:65], v213, vcc_lo
	v_cmp_ge_u32_e64 s[66:67], v212, vcc_lo
	v_cmp_ge_u32_e64 s[68:69], v211, vcc_lo
	v_cmp_ge_u32_e64 s[70:71], v210, vcc_lo
	v_cmp_ge_u32_e64 s[72:73], v207, vcc_lo
	v_cmp_ge_u32_e64 s[74:75], v194, vcc_lo
	v_addc_co_u32_e64 v242, s[42:43], 0, v242, s[42:43]
	v_addc_co_u32_e64 v242, s[62:63], 0, v242, s[62:63]
	v_addc_co_u32_e64 v242, s[64:65], 0, v242, s[64:65]
	v_addc_co_u32_e64 v242, s[66:67], 0, v242, s[66:67]
	v_addc_co_u32_e64 v242, s[68:69], 0, v242, s[68:69]
	v_addc_co_u32_e64 v242, s[70:71], 0, v242, s[70:71]
	v_addc_co_u32_e64 v242, s[72:73], 0, v242, s[72:73]
	v_addc_co_u32_e64 v242, s[74:75], 0, v242, s[74:75]
	v_cmp_ge_u32_e64 s[42:43], v195, vcc_lo
	v_cmp_ge_u32_e64 s[62:63], v193, vcc_lo
	v_cmp_ge_u32_e64 s[64:65], v192, vcc_lo
	v_cmp_ge_u32_e64 s[66:67], v191, vcc_lo
	v_cmp_ge_u32_e64 s[68:69], v190, vcc_lo
	v_cmp_ge_u32_e64 s[70:71], v189, vcc_lo
	v_cmp_ge_u32_e64 s[72:73], v188, vcc_lo
	v_cmp_ge_u32_e64 s[74:75], v186, vcc_lo
	v_addc_co_u32_e64 v242, s[42:43], 0, v242, s[42:43]
	v_addc_co_u32_e64 v242, s[62:63], 0, v242, s[62:63]
	v_addc_co_u32_e64 v242, s[64:65], 0, v242, s[64:65]
	v_addc_co_u32_e64 v242, s[66:67], 0, v242, s[66:67]
	v_addc_co_u32_e64 v242, s[68:69], 0, v242, s[68:69]
	v_addc_co_u32_e64 v242, s[70:71], 0, v242, s[70:71]
	v_addc_co_u32_e64 v242, s[72:73], 0, v242, s[72:73]
	v_addc_co_u32_e64 v242, s[74:75], 0, v242, s[74:75]
	v_cmp_ge_u32_e64 s[42:43], v187, vcc_lo
	v_cmp_ge_u32_e64 s[62:63], v185, vcc_lo
	v_cmp_ge_u32_e64 s[64:65], v184, vcc_lo
	v_cmp_ge_u32_e64 s[66:67], v183, vcc_lo
	v_cmp_ge_u32_e64 s[68:69], v182, vcc_lo
	v_cmp_ge_u32_e64 s[70:71], v181, vcc_lo
	v_cmp_ge_u32_e64 s[72:73], v180, vcc_lo
	v_cmp_ge_u32_e64 s[74:75], v178, vcc_lo
	v_addc_co_u32_e64 v242, s[42:43], 0, v242, s[42:43]
	v_addc_co_u32_e64 v242, s[62:63], 0, v242, s[62:63]
	v_addc_co_u32_e64 v242, s[64:65], 0, v242, s[64:65]
	v_addc_co_u32_e64 v242, s[66:67], 0, v242, s[66:67]
	v_addc_co_u32_e64 v242, s[68:69], 0, v242, s[68:69]
	v_addc_co_u32_e64 v242, s[70:71], 0, v242, s[70:71]
	v_addc_co_u32_e64 v242, s[72:73], 0, v242, s[72:73]
	v_addc_co_u32_e64 v242, s[74:75], 0, v242, s[74:75]
	s_nop 1
	v_add_u32_dpp v242, v242, v242 row_shr:1 row_mask:0xf bank_mask:0xf bound_ctrl:1
	s_nop 1
	v_add_u32_dpp v242, v242, v242 row_shr:2 row_mask:0xf bank_mask:0xf bound_ctrl:1
	s_nop 1
	v_add_u32_dpp v242, v242, v242 row_shr:4 row_mask:0xf bank_mask:0xf bound_ctrl:1
	s_nop 1
	v_add_u32_dpp v242, v242, v242 row_shr:8 row_mask:0xf bank_mask:0xf bound_ctrl:1
	s_nop 0
	v_readlane_b32 s42, v242, 15
	v_readlane_b32 s43, v242, 31
	s_add_i32 s42, s43, s42
	v_readlane_b32 s43, v242, 47
	s_add_i32 s42, s42, s43
	v_readlane_b32 s43, v242, 63
	s_add_i32 s42, s42, s43
	s_cmpk_gt_i32 s42, 0xff
	s_cselect_b32 s59, s42, s59
	s_cselect_b32 s101, vcc_lo, s101
	s_cmpk_eq_i32 s42, 0x100
	s_cbranch_scc1 .Lselq1_exit
	s_lshr_b32 vcc_hi, vcc_hi, 1
	s_cmp_lg_u32 vcc_hi, 0
	s_cbranch_scc1 .Lselq1_top

; template <int NB>
; __device__ __forceinline__ void bisect256(const unsigned (&x)[64], unsigned& tau_out, int& cge_out) {
;     ...
;     const unsigned cand = tau | (1u << bit);
;     unsigned cl = 0u;
; #pragma unroll
;     for (int blk = 0; blk < NB; ++blk) {
;       unsigned long long m0, m1, m2, m3, m4, m5, m6, m7;
;       asm volatile(
;           "v_cmp_ge_u32_e64 %1, %9, %17\n\tv_cmp_ge_u32_e64 %2, %10, %17\n\tv_cmp_ge_u32_e64 %3, %11, %17\n\tv_cmp_ge_u32_e64 %4, %12, %17\n\t"
;           "v_cmp_ge_u32_e64 %5, %13, %17\n\tv_cmp_ge_u32_e64 %6, %14, %17\n\tv_cmp_ge_u32_e64 %7, %15, %17\n\tv_cmp_ge_u32_e64 %8, %16, %17\n\t"
;           "v_addc_co_u32_e64 %0, %1, 0, %0, %1\n\tv_addc_co_u32_e64 %0, %2, 0, %0, %2\n\tv_addc_co_u32_e64 %0, %3, 0, %0, %3\n\t"
;           "v_addc_co_u32_e64 %0, %4, 0, %0, %4\n\tv_addc_co_u32_e64 %0, %5, 0, %0, %5\n\tv_addc_co_u32_e64 %0, %6, 0, %0, %6\n\t"
;           "v_addc_co_u32_e64 %0, %7, 0, %0, %7\n\tv_addc_co_u32_e64 %0, %8, 0, %0, %8"
;           : "+v"(cl), "=&s"(m0), "=&s"(m1), "=&s"(m2), "=&s"(m3), "=&s"(m4), "=&s"(m5), "=&s"(m6), "=&s"(m7)
;           : "v"(x[blk * 8 + 0]), "v"(x[blk * 8 + 1]), "v"(x[blk * 8 + 2]), "v"(x[blk * 8 + 3]), "v"(x[blk * 8 + 4]), "v"(x[blk * 8 + 5]),
;             "v"(x[blk * 8 + 6]), "v"(x[blk * 8 + 7]), "v"(cand));
;     }
;     cl += (unsigned)__builtin_amdgcn_update_dpp(0, (int)cl, 0x111, 0xf, 0xf, true);
;     cl += (unsigned)__builtin_amdgcn_update_dpp(0, (int)cl, 0x112, 0xf, 0xf, true);
;     cl += (unsigned)__builtin_amdgcn_update_dpp(0, (int)cl, 0x114, 0xf, 0xf, true);
;     cl += (unsigned)__builtin_amdgcn_update_dpp(0, (int)cl, 0x118, 0xf, 0xf, true);
;     const int cnt = __builtin_amdgcn_readlane((int)cl, 15) + __builtin_amdgcn_readlane((int)cl, 31) + __builtin_amdgcn_readlane((int)cl, 47) +
;                     __builtin_amdgcn_readlane((int)cl, 63);
;     if (cnt >= 256) { tau = cand; cge = cnt; }
;     if (cnt == 256) break;
;   }
.LBB0_2948:
	s_cmp_gt_i32 s61, 4
	s_cbranch_scc0 .LBB0_2952
	s_mov_b32 s59, 0
	s_mov_b32 s101, 0
	s_mov_b32 vcc_hi, 0x80000000
.Lselq2_top:
	s_or_b32 vcc_lo, s101, vcc_hi
	v_mov_b32_e32 v242, v17
	v_cmp_ge_u32_e64 s[42:43], v239, vcc_lo
	v_cmp_ge_u32_e64 s[62:63], v238, vcc_lo
	v_cmp_ge_u32_e64 s[64:65], v237, vcc_lo
	v_cmp_ge_u32_e64 s[66:67], v236, vcc_lo
	v_cmp_ge_u32_e64 s[68:69], v235, vcc_lo
	v_cmp_ge_u32_e64 s[70:71], v234, vcc_lo
	v_cmp_ge_u32_e64 s[72:73], v233, vcc_lo
	v_cmp_ge_u32_e64 s[74:75], v231, vcc_lo
	v_addc_co_u32_e64 v242, s[42:43], 0, v242, s[42:43]
	v_addc_co_u32_e64 v242, s[62:63], 0, v242, s[62:63]
	v_addc_co_u32_e64 v242, s[64:65], 0, v242, s[64:65]
	v_addc_co_u32_e64 v242, s[66:67], 0, v242, s[66:67]
	v_addc_co_u32_e64 v242, s[68:69], 0, v242, s[68:69]
	v_addc_co_u32_e64 v242, s[70:71], 0, v242, s[70:71]
	v_addc_co_u32_e64 v242, s[72:73], 0, v242, s[72:73]
	v_addc_co_u32_e64 v242, s[74:75], 0, v242, s[74:75]
	v_cmp_ge_u32_e64 s[42:43], v232, vcc_lo
	v_cmp_ge_u32_e64 s[62:63], v230, vcc_lo
	v_cmp_ge_u32_e64 s[64:65], v229, vcc_lo
	v_cmp_ge_u32_e64 s[66:67], v228, vcc_lo
	v_cmp_ge_u32_e64 s[68:69], v227, vcc_lo
	v_cmp_ge_u32_e64 s[70:71], v226, vcc_lo
	v_cmp_ge_u32_e64 s[72:73], v225, vcc_lo
	v_cmp_ge_u32_e64 s[74:75], v223, vcc_lo
	v_addc_co_u32_e64 v242, s[42:43], 0, v242, s[42:43]
	v_addc_co_u32_e64 v242, s[62:63], 0, v242, s[62:63]
	v_addc_co_u32_e64 v242, s[64:65], 0, v242, s[64:65]
	v_addc_co_u32_e64 v242, s[66:67], 0, v242, s[66:67]
	v_addc_co_u32_e64 v242, s[68:69], 0, v242, s[68:69]
	v_addc_co_u32_e64 v242, s[70:71], 0, v242, s[70:71]
	v_addc_co_u32_e64 v242, s[72:73], 0, v242, s[72:73]
	v_addc_co_u32_e64 v242, s[74:75], 0, v242, s[74:75]
	v_cmp_ge_u32_e64 s[42:43], v224, vcc_lo
	v_cmp_ge_u32_e64 s[62:63], v222, vcc_lo
	v_cmp_ge_u32_e64 s[64:65], v221, vcc_lo
	v_cmp_ge_u32_e64 s[66:67], v220, vcc_lo
	v_cmp_ge_u32_e64 s[68:69], v219, vcc_lo
	v_cmp_ge_u32_e64 s[70:71], v218, vcc_lo
	v_cmp_ge_u32_e64 s[72:73], v217, vcc_lo
	v_cmp_ge_u32_e64 s[74:75], v215, vcc_lo
	v_addc_co_u32_e64 v242, s[42:43], 0, v242, s[42:43]
	v_addc_co_u32_e64 v242, s[62:63], 0, v242, s[62:63]
	v_addc_co_u32_e64 v242, s[64:65], 0, v242, s[64:65]
	v_addc_co_u32_e64 v242, s[66:67], 0, v242, s[66:67]
	v_addc_co_u32_e64 v242, s[68:69], 0, v242, s[68:69]
	v_addc_co_u32_e64 v242, s[70:71], 0, v242, s[70:71]
	v_addc_co_u32_e64 v242, s[72:73], 0, v242, s[72:73]
	v_addc_co_u32_e64 v242, s[74:75], 0, v242, s[74:75]
	v_cmp_ge_u32_e64 s[42:43], v216, vcc_lo
	v_cmp_ge_u32_e64 s[62:63], v214, vcc_lo
	v_cmp_ge_u32_e64 s[64:65], v213, vcc_lo
	v_cmp_ge_u32_e64 s[66:67], v212, vcc_lo
	v_cmp_ge_u32_e64 s[68:69], v211, vcc_lo
	v_cmp_ge_u32_e64 s[70:71], v210, vcc_lo
	v_cmp_ge_u32_e64 s[72:73], v207, vcc_lo
	v_cmp_ge_u32_e64 s[74:75], v194, vcc_lo
	v_addc_co_u32_e64 v242, s[42:43], 0, v242, s[42:43]
	v_addc_co_u32_e64 v242, s[62:63], 0, v242, s[62:63]
	v_addc_co_u32_e64 v242, s[64:65], 0, v242, s[64:65]
	v_addc_co_u32_e64 v242, s[66:67], 0, v242, s[66:67]
	v_addc_co_u32_e64 v242, s[68:69], 0, v242, s[68:69]
	v_addc_co_u32_e64 v242, s[70:71], 0, v242, s[70:71]
	v_addc_co_u32_e64 v242, s[72:73], 0, v242, s[72:73]
	v_addc_co_u32_e64 v242, s[74:75], 0, v242, s[74:75]
	v_cmp_ge_u32_e64 s[42:43], v195, vcc_lo
	v_cmp_ge_u32_e64 s[62:63], v193, vcc_lo
	v_cmp_ge_u32_e64 s[64:65], v192, vcc_lo
	v_cmp_ge_u32_e64 s[66:67], v191, vcc_lo
	v_cmp_ge_u32_e64 s[68:69], v190, vcc_lo
	v_cmp_ge_u32_e64 s[70:71], v189, vcc_lo
	v_cmp_ge_u32_e64 s[72:73], v188, vcc_lo
	v_cmp_ge_u32_e64 s[74:75], v186, vcc_lo
	v_addc_co_u32_e64 v242, s[42:43], 0, v242, s[42:43]
	v_addc_co_u32_e64 v242, s[62:63], 0, v242, s[62:63]
	v_addc_co_u32_e64 v242, s[64:65], 0, v242, s[64:65]
	v_addc_co_u32_e64 v242, s[66:67], 0, v242, s[66:67]
	v_addc_co_u32_e64 v242, s[68:69], 0, v242, s[68:69]
	v_addc_co_u32_e64 v242, s[70:71], 0, v242, s[70:71]
	v_addc_co_u32_e64 v242, s[72:73], 0, v242, s[72:73]
	v_addc_co_u32_e64 v242, s[74:75], 0, v242, s[74:75]
	s_nop 1
	v_add_u32_dpp v242, v242, v242 row_shr:1 row_mask:0xf bank_mask:0xf bound_ctrl:1
	s_nop 1
	v_add_u32_dpp v242, v242, v242 row_shr:2 row_mask:0xf bank_mask:0xf bound_ctrl:1
	s_nop 1
	v_add_u32_dpp v242, v242, v242 row_shr:4 row_mask:0xf bank_mask:0xf bound_ctrl:1
	s_nop 1
	v_add_u32_dpp v242, v242, v242 row_shr:8 row_mask:0xf bank_mask:0xf bound_ctrl:1
	s_nop 0
	v_readlane_b32 s42, v242, 15
	v_readlane_b32 s43, v242, 31
	s_add_i32 s42, s43, s42
	v_readlane_b32 s43, v242, 47
	s_add_i32 s42, s42, s43
	v_readlane_b32 s43, v242, 63
	s_add_i32 s42, s42, s43
	s_cmpk_gt_i32 s42, 0xff
	s_cselect_b32 s59, s42, s59
	s_cselect_b32 s101, vcc_lo, s101
	s_cmpk_eq_i32 s42, 0x100
	s_cbranch_scc1 .Lselq2_exit
	s_lshr_b32 vcc_hi, vcc_hi, 1
	s_cmp_lg_u32 vcc_hi, 0
	s_cbranch_scc1 .Lselq2_top

; template <int NB>
; __device__ __forceinline__ void bisect256(const unsigned (&x)[64], unsigned& tau_out, int& cge_out) {
;     ...
;     const unsigned cand = tau | (1u << bit);
;     unsigned cl = 0u;
; #pragma unroll
;     for (int blk = 0; blk < NB; ++blk) {
;       unsigned long long m0, m1, m2, m3, m4, m5, m6, m7;
;       asm volatile(
;           "v_cmp_ge_u32_e64 %1, %9, %17\n\tv_cmp_ge_u32_e64 %2, %10, %17\n\tv_cmp_ge_u32_e64 %3, %11, %17\n\tv_cmp_ge_u32_e64 %4, %12, %17\n\t"
;           "v_cmp_ge_u32_e64 %5, %13, %17\n\tv_cmp_ge_u32_e64 %6, %14, %17\n\tv_cmp_ge_u32_e64 %7, %15, %17\n\tv_cmp_ge_u32_e64 %8, %16, %17\n\t"
;           "v_addc_co_u32_e64 %0, %1, 0, %0, %1\n\tv_addc_co_u32_e64 %0, %2, 0, %0, %2\n\tv_addc_co_u32_e64 %0, %3, 0, %0, %3\n\t"
;           "v_addc_co_u32_e64 %0, %4, 0, %0, %4\n\tv_addc_co_u32_e64 %0, %5, 0, %0, %5\n\tv_addc_co_u32_e64 %0, %6, 0, %0, %6\n\t"
;           "v_addc_co_u32_e64 %0, %7, 0, %0, %7\n\tv_addc_co_u32_e64 %0, %8, 0, %0, %8"
;           : "+v"(cl), "=&s"(m0), "=&s"(m1), "=&s"(m2), "=&s"(m3), "=&s"(m4), "=&s"(m5), "=&s"(m6), "=&s"(m7)
;           : "v"(x[blk * 8 + 0]), "v"(x[blk * 8 + 1]), "v"(x[blk * 8 + 2]), "v"(x[blk * 8 + 3]), "v"(x[blk * 8 + 4]), "v"(x[blk * 8 + 5]),
;             "v"(x[blk * 8 + 6]), "v"(x[blk * 8 + 7]), "v"(cand));
;     }
;     cl += (unsigned)__builtin_amdgcn_update_dpp(0, (int)cl, 0x111, 0xf, 0xf, true);
;     cl += (unsigned)__builtin_amdgcn_update_dpp(0, (int)cl, 0x112, 0xf, 0xf, true);
;     cl += (unsigned)__builtin_amdgcn_update_dpp(0, (int)cl, 0x114, 0xf, 0xf, true);
;     cl += (unsigned)__builtin_amdgcn_update_dpp(0, (int)cl, 0x118, 0xf, 0xf, true);
;     const int cnt = __builtin_amdgcn_readlane((int)cl, 15) + __builtin_amdgcn_readlane((int)cl, 31) + __builtin_amdgcn_readlane((int)cl, 47) +
;                     __builtin_amdgcn_readlane((int)cl, 63);
;     if (cnt >= 256) { tau = cand; cge = cnt; }
;     if (cnt == 256) break;
;   }
.LBB0_2952:
	s_cbranch_execz .LBB0_2955
	s_mov_b32 s59, 0
	s_mov_b32 s101, 0
	s_mov_b32 vcc_hi, 0x80000000
.Lselq3_top:
	s_or_b32 vcc_lo, s101, vcc_hi
	v_mov_b32_e32 v242, v17
	v_cmp_ge_u32_e64 s[42:43], v239, vcc_lo
	v_cmp_ge_u32_e64 s[62:63], v238, vcc_lo
	v_cmp_ge_u32_e64 s[64:65], v237, vcc_lo
	v_cmp_ge_u32_e64 s[66:67], v236, vcc_lo
	v_cmp_ge_u32_e64 s[68:69], v235, vcc_lo
	v_cmp_ge_u32_e64 s[70:71], v234, vcc_lo
	v_cmp_ge_u32_e64 s[72:73], v233, vcc_lo
	v_cmp_ge_u32_e64 s[74:75], v231, vcc_lo
	v_addc_co_u32_e64 v242, s[42:43], 0, v242, s[42:43]
	v_addc_co_u32_e64 v242, s[62:63], 0, v242, s[62:63]
	v_addc_co_u32_e64 v242, s[64:65], 0, v242, s[64:65]
	v_addc_co_u32_e64 v242, s[66:67], 0, v242, s[66:67]
	v_addc_co_u32_e64 v242, s[68:69], 0, v242, s[68:69]
	v_addc_co_u32_e64 v242, s[70:71], 0, v242, s[70:71]
	v_addc_co_u32_e64 v242, s[72:73], 0, v242, s[72:73]
	v_addc_co_u32_e64 v242, s[74:75], 0, v242, s[74:75]
	v_cmp_ge_u32_e64 s[42:43], v232, vcc_lo
	v_cmp_ge_u32_e64 s[62:63], v230, vcc_lo
	v_cmp_ge_u32_e64 s[64:65], v229, vcc_lo
	v_cmp_ge_u32_e64 s[66:67], v228, vcc_lo
	v_cmp_ge_u32_e64 s[68:69], v227, vcc_lo
	v_cmp_ge_u32_e64 s[70:71], v226, vcc_lo
	v_cmp_ge_u32_e64 s[72:73], v225, vcc_lo
	v_cmp_ge_u32_e64 s[74:75], v223, vcc_lo
	v_addc_co_u32_e64 v242, s[42:43], 0, v242, s[42:43]
	v_addc_co_u32_e64 v242, s[62:63], 0, v242, s[62:63]
	v_addc_co_u32_e64 v242, s[64:65], 0, v242, s[64:65]
	v_addc_co_u32_e64 v242, s[66:67], 0, v242, s[66:67]
	v_addc_co_u32_e64 v242, s[68:69], 0, v242, s[68:69]
	v_addc_co_u32_e64 v242, s[70:71], 0, v242, s[70:71]
	v_addc_co_u32_e64 v242, s[72:73], 0, v242, s[72:73]
	v_addc_co_u32_e64 v242, s[74:75], 0, v242, s[74:75]
	v_cmp_ge_u32_e64 s[42:43], v224, vcc_lo
	v_cmp_ge_u32_e64 s[62:63], v222, vcc_lo
	v_cmp_ge_u32_e64 s[64:65], v221, vcc_lo
	v_cmp_ge_u32_e64 s[66:67], v220, vcc_lo
	v_cmp_ge_u32_e64 s[68:69], v219, vcc_lo
	v_cmp_ge_u32_e64 s[70:71], v218, vcc_lo
	v_cmp_ge_u32_e64 s[72:73], v217, vcc_lo
	v_cmp_ge_u32_e64 s[74:75], v215, vcc_lo
	v_addc_co_u32_e64 v242, s[42:43], 0, v242, s[42:43]
	v_addc_co_u32_e64 v242, s[62:63], 0, v242, s[62:63]
	v_addc_co_u32_e64 v242, s[64:65], 0, v242, s[64:65]
	v_addc_co_u32_e64 v242, s[66:67], 0, v242, s[66:67]
	v_addc_co_u32_e64 v242, s[68:69], 0, v242, s[68:69]
	v_addc_co_u32_e64 v242, s[70:71], 0, v242, s[70:71]
	v_addc_co_u32_e64 v242, s[72:73], 0, v242, s[72:73]
	v_addc_co_u32_e64 v242, s[74:75], 0, v242, s[74:75]
	v_cmp_ge_u32_e64 s[42:43], v216, vcc_lo
	v_cmp_ge_u32_e64 s[62:63], v214, vcc_lo
	v_cmp_ge_u32_e64 s[64:65], v213, vcc_lo
	v_cmp_ge_u32_e64 s[66:67], v212, vcc_lo
	v_cmp_ge_u32_e64 s[68:69], v211, vcc_lo
	v_cmp_ge_u32_e64 s[70:71], v210, vcc_lo
	v_cmp_ge_u32_e64 s[72:73], v207, vcc_lo
	v_cmp_ge_u32_e64 s[74:75], v194, vcc_lo
	v_addc_co_u32_e64 v242, s[42:43], 0, v242, s[42:43]
	v_addc_co_u32_e64 v242, s[62:63], 0, v242, s[62:63]
	v_addc_co_u32_e64 v242, s[64:65], 0, v242, s[64:65]
	v_addc_co_u32_e64 v242, s[66:67], 0, v242, s[66:67]
	v_addc_co_u32_e64 v242, s[68:69], 0, v242, s[68:69]
	v_addc_co_u32_e64 v242, s[70:71], 0, v242, s[70:71]
	v_addc_co_u32_e64 v242, s[72:73], 0, v242, s[72:73]
	v_addc_co_u32_e64 v242, s[74:75], 0, v242, s[74:75]
	s_nop 1
	v_add_u32_dpp v242, v242, v242 row_shr:1 row_mask:0xf bank_mask:0xf bound_ctrl:1
	s_nop 1
	v_add_u32_dpp v242, v242, v242 row_shr:2 row_mask:0xf bank_mask:0xf bound_ctrl:1
	s_nop 1
	v_add_u32_dpp v242, v242, v242 row_shr:4 row_mask:0xf bank_mask:0xf bound_ctrl:1
	s_nop 1
	v_add_u32_dpp v242, v242, v242 row_shr:8 row_mask:0xf bank_mask:0xf bound_ctrl:1
	s_nop 0
	v_readlane_b32 s42, v242, 15
	v_readlane_b32 s43, v242, 31
	s_add_i32 s42, s43, s42
	v_readlane_b32 s43, v242, 47
	s_add_i32 s42, s42, s43
	v_readlane_b32 s43, v242, 63
	s_add_i32 s42, s42, s43
	s_cmpk_gt_i32 s42, 0xff
	s_cselect_b32 s59, s42, s59
	s_cselect_b32 s101, vcc_lo, s101
	s_cmpk_eq_i32 s42, 0x100
	s_cbranch_scc1 .Lselq3_exit
	s_lshr_b32 vcc_hi, vcc_hi, 1
	s_cmp_lg_u32 vcc_hi, 0
	s_cbranch_scc1 .Lselq3_top

; template <int NB>
; __device__ __forceinline__ void bisect256(const unsigned (&x)[64], unsigned& tau_out, int& cge_out) {
;     ...
;     const unsigned cand = tau | (1u << bit);
;     unsigned cl = 0u;
; #pragma unroll
;     for (int blk = 0; blk < NB; ++blk) {
;       unsigned long long m0, m1, m2, m3, m4, m5, m6, m7;
;       asm volatile(
;           "v_cmp_ge_u32_e64 %1, %9, %17\n\tv_cmp_ge_u32_e64 %2, %10, %17\n\tv_cmp_ge_u32_e64 %3, %11, %17\n\tv_cmp_ge_u32_e64 %4, %12, %17\n\t"
;           "v_cmp_ge_u32_e64 %5, %13, %17\n\tv_cmp_ge_u32_e64 %6, %14, %17\n\tv_cmp_ge_u32_e64 %7, %15, %17\n\tv_cmp_ge_u32_e64 %8, %16, %17\n\t"
;           "v_addc_co_u32_e64 %0, %1, 0, %0, %1\n\tv_addc_co_u32_e64 %0, %2, 0, %0, %2\n\tv_addc_co_u32_e64 %0, %3, 0, %0, %3\n\t"
;           "v_addc_co_u32_e64 %0, %4, 0, %0, %4\n\tv_addc_co_u32_e64 %0, %5, 0, %0, %5\n\tv_addc_co_u32_e64 %0, %6, 0, %0, %6\n\t"
;           "v_addc_co_u32_e64 %0, %7, 0, %0, %7\n\tv_addc_co_u32_e64 %0, %8, 0, %0, %8"
;           : "+v"(cl), "=&s"(m0), "=&s"(m1), "=&s"(m2), "=&s"(m3), "=&s"(m4), "=&s"(m5), "=&s"(m6), "=&s"(m7)
;           : "v"(x[blk * 8 + 0]), "v"(x[blk * 8 + 1]), "v"(x[blk * 8 + 2]), "v"(x[blk * 8 + 3]), "v"(x[blk * 8 + 4]), "v"(x[blk * 8 + 5]),
;             "v"(x[blk * 8 + 6]), "v"(x[blk * 8 + 7]), "v"(cand));
;     }
;     cl += (unsigned)__builtin_amdgcn_update_dpp(0, (int)cl, 0x111, 0xf, 0xf, true);
;     cl += (unsigned)__builtin_amdgcn_update_dpp(0, (int)cl, 0x112, 0xf, 0xf, true);
;     cl += (unsigned)__builtin_amdgcn_update_dpp(0, (int)cl, 0x114, 0xf, 0xf, true);
;     cl += (unsigned)__builtin_amdgcn_update_dpp(0, (int)cl, 0x118, 0xf, 0xf, true);
;     const int cnt = __builtin_amdgcn_readlane((int)cl, 15) + __builtin_amdgcn_readlane((int)cl, 31) + __builtin_amdgcn_readlane((int)cl, 47) +
;                     __builtin_amdgcn_readlane((int)cl, 63);
;     if (cnt >= 256) { tau = cand; cge = cnt; }
;     if (cnt == 256) break;
;   }
.LBB0_2956:
	s_cmp_gt_i32 s61, 1
	s_cbranch_scc0 .LBB0_2961
	s_cmp_gt_i32 s61, 2
	s_cbranch_scc0 .LBB0_2962
	s_mov_b32 s59, 0
	s_mov_b32 s101, 0
	s_mov_b32 vcc_hi, 0x80000000
.Lselq4_top:
	s_or_b32 vcc_lo, s101, vcc_hi
	v_mov_b32_e32 v242, v17
	v_cmp_ge_u32_e64 s[40:41], v239, vcc_lo
	v_cmp_ge_u32_e64 s[42:43], v238, vcc_lo
	v_cmp_ge_u32_e64 s[62:63], v237, vcc_lo
	v_cmp_ge_u32_e64 s[64:65], v236, vcc_lo
	v_cmp_ge_u32_e64 s[66:67], v235, vcc_lo
	v_cmp_ge_u32_e64 s[68:69], v234, vcc_lo
	v_cmp_ge_u32_e64 s[70:71], v233, vcc_lo
	v_cmp_ge_u32_e64 s[72:73], v231, vcc_lo
	v_addc_co_u32_e64 v242, s[40:41], 0, v242, s[40:41]
	v_addc_co_u32_e64 v242, s[42:43], 0, v242, s[42:43]
	v_addc_co_u32_e64 v242, s[62:63], 0, v242, s[62:63]
	v_addc_co_u32_e64 v242, s[64:65], 0, v242, s[64:65]
	v_addc_co_u32_e64 v242, s[66:67], 0, v242, s[66:67]
	v_addc_co_u32_e64 v242, s[68:69], 0, v242, s[68:69]
	v_addc_co_u32_e64 v242, s[70:71], 0, v242, s[70:71]
	v_addc_co_u32_e64 v242, s[72:73], 0, v242, s[72:73]
	v_cmp_ge_u32_e64 s[40:41], v232, vcc_lo
	v_cmp_ge_u32_e64 s[42:43], v230, vcc_lo
	v_cmp_ge_u32_e64 s[62:63], v229, vcc_lo
	v_cmp_ge_u32_e64 s[64:65], v228, vcc_lo
	v_cmp_ge_u32_e64 s[66:67], v227, vcc_lo
	v_cmp_ge_u32_e64 s[68:69], v226, vcc_lo
	v_cmp_ge_u32_e64 s[70:71], v225, vcc_lo
	v_cmp_ge_u32_e64 s[72:73], v223, vcc_lo
	v_addc_co_u32_e64 v242, s[40:41], 0, v242, s[40:41]
	v_addc_co_u32_e64 v242, s[42:43], 0, v242, s[42:43]
	v_addc_co_u32_e64 v242, s[62:63], 0, v242, s[62:63]
	v_addc_co_u32_e64 v242, s[64:65], 0, v242, s[64:65]
	v_addc_co_u32_e64 v242, s[66:67], 0, v242, s[66:67]
	v_addc_co_u32_e64 v242, s[68:69], 0, v242, s[68:69]
	v_addc_co_u32_e64 v242, s[70:71], 0, v242, s[70:71]
	v_addc_co_u32_e64 v242, s[72:73], 0, v242, s[72:73]
	v_cmp_ge_u32_e64 s[40:41], v224, vcc_lo
	v_cmp_ge_u32_e64 s[42:43], v222, vcc_lo
	v_cmp_ge_u32_e64 s[62:63], v221, vcc_lo
	v_cmp_ge_u32_e64 s[64:65], v220, vcc_lo
	v_cmp_ge_u32_e64 s[66:67], v219, vcc_lo
	v_cmp_ge_u32_e64 s[68:69], v218, vcc_lo
	v_cmp_ge_u32_e64 s[70:71], v217, vcc_lo
	v_cmp_ge_u32_e64 s[72:73], v215, vcc_lo
	v_addc_co_u32_e64 v242, s[40:41], 0, v242, s[40:41]
	v_addc_co_u32_e64 v242, s[42:43], 0, v242, s[42:43]
	v_addc_co_u32_e64 v242, s[62:63], 0, v242, s[62:63]
	v_addc_co_u32_e64 v242, s[64:65], 0, v242, s[64:65]
	v_addc_co_u32_e64 v242, s[66:67], 0, v242, s[66:67]
	v_addc_co_u32_e64 v242, s[68:69], 0, v242, s[68:69]
	v_addc_co_u32_e64 v242, s[70:71], 0, v242, s[70:71]
	v_addc_co_u32_e64 v242, s[72:73], 0, v242, s[72:73]
	s_nop 1
	v_add_u32_dpp v242, v242, v242 row_shr:1 row_mask:0xf bank_mask:0xf bound_ctrl:1
	s_nop 1
	v_add_u32_dpp v242, v242, v242 row_shr:2 row_mask:0xf bank_mask:0xf bound_ctrl:1
	s_nop 1
	v_add_u32_dpp v242, v242, v242 row_shr:4 row_mask:0xf bank_mask:0xf bound_ctrl:1
	s_nop 1
	v_add_u32_dpp v242, v242, v242 row_shr:8 row_mask:0xf bank_mask:0xf bound_ctrl:1
	s_nop 0
	v_readlane_b32 s40, v242, 15
	v_readlane_b32 s41, v242, 31
	s_add_i32 s40, s41, s40
	v_readlane_b32 s41, v242, 47
	s_add_i32 s40, s40, s41
	v_readlane_b32 s41, v242, 63
	s_add_i32 s40, s40, s41
	s_cmpk_gt_i32 s40, 0xff
	s_cselect_b32 s59, s40, s59
	s_cselect_b32 s101, vcc_lo, s101
	s_cmpk_eq_i32 s40, 0x100
	s_cbranch_scc1 .Lselq4_exit
	s_lshr_b32 vcc_hi, vcc_hi, 1
	s_cmp_lg_u32 vcc_hi, 0
	s_cbranch_scc1 .Lselq4_top

; template <int NB>
; __device__ __forceinline__ void bisect256(const unsigned (&x)[64], unsigned& tau_out, int& cge_out) {
;     ...
;     const unsigned cand = tau | (1u << bit);
;     unsigned cl = 0u;
; #pragma unroll
;     for (int blk = 0; blk < NB; ++blk) {
;       unsigned long long m0, m1, m2, m3, m4, m5, m6, m7;
;       asm volatile(
;           "v_cmp_ge_u32_e64 %1, %9, %17\n\tv_cmp_ge_u32_e64 %2, %10, %17\n\tv_cmp_ge_u32_e64 %3, %11, %17\n\tv_cmp_ge_u32_e64 %4, %12, %17\n\t"
;           "v_cmp_ge_u32_e64 %5, %13, %17\n\tv_cmp_ge_u32_e64 %6, %14, %17\n\tv_cmp_ge_u32_e64 %7, %15, %17\n\tv_cmp_ge_u32_e64 %8, %16, %17\n\t"
;           "v_addc_co_u32_e64 %0, %1, 0, %0, %1\n\tv_addc_co_u32_e64 %0, %2, 0, %0, %2\n\tv_addc_co_u32_e64 %0, %3, 0, %0, %3\n\t"
;           "v_addc_co_u32_e64 %0, %4, 0, %0, %4\n\tv_addc_co_u32_e64 %0, %5, 0, %0, %5\n\tv_addc_co_u32_e64 %0, %6, 0, %0, %6\n\t"
;           "v_addc_co_u32_e64 %0, %7, 0, %0, %7\n\tv_addc_co_u32_e64 %0, %8, 0, %0, %8"
;           : "+v"(cl), "=&s"(m0), "=&s"(m1), "=&s"(m2), "=&s"(m3), "=&s"(m4), "=&s"(m5), "=&s"(m6), "=&s"(m7)
;           : "v"(x[blk * 8 + 0]), "v"(x[blk * 8 + 1]), "v"(x[blk * 8 + 2]), "v"(x[blk * 8 + 3]), "v"(x[blk * 8 + 4]), "v"(x[blk * 8 + 5]),
;             "v"(x[blk * 8 + 6]), "v"(x[blk * 8 + 7]), "v"(cand));
;     }
;     cl += (unsigned)__builtin_amdgcn_update_dpp(0, (int)cl, 0x111, 0xf, 0xf, true);
;     cl += (unsigned)__builtin_amdgcn_update_dpp(0, (int)cl, 0x112, 0xf, 0xf, true);
;     cl += (unsigned)__builtin_amdgcn_update_dpp(0, (int)cl, 0x114, 0xf, 0xf, true);
;     cl += (unsigned)__builtin_amdgcn_update_dpp(0, (int)cl, 0x118, 0xf, 0xf, true);
;     const int cnt = __builtin_amdgcn_readlane((int)cl, 15) + __builtin_amdgcn_readlane((int)cl, 31) + __builtin_amdgcn_readlane((int)cl, 47) +
;                     __builtin_amdgcn_readlane((int)cl, 63);
;     if (cnt >= 256) { tau = cand; cge = cnt; }
;     if (cnt == 256) break;
;   }
.Lselq5_top:
	s_or_b32 vcc_lo, s101, vcc_hi
	v_mov_b32_e32 v242, v17
	v_cmp_ge_u32_e64 s[40:41], v239, vcc_lo
	v_cmp_ge_u32_e64 s[42:43], v238, vcc_lo
	v_cmp_ge_u32_e64 s[62:63], v237, vcc_lo
	v_cmp_ge_u32_e64 s[64:65], v236, vcc_lo
	v_cmp_ge_u32_e64 s[66:67], v235, vcc_lo
	v_cmp_ge_u32_e64 s[68:69], v234, vcc_lo
	v_cmp_ge_u32_e64 s[70:71], v233, vcc_lo
	v_cmp_ge_u32_e64 s[72:73], v231, vcc_lo
	v_addc_co_u32_e64 v242, s[40:41], 0, v242, s[40:41]
	v_addc_co_u32_e64 v242, s[42:43], 0, v242, s[42:43]
	v_addc_co_u32_e64 v242, s[62:63], 0, v242, s[62:63]
	v_addc_co_u32_e64 v242, s[64:65], 0, v242, s[64:65]
	v_addc_co_u32_e64 v242, s[66:67], 0, v242, s[66:67]
	v_addc_co_u32_e64 v242, s[68:69], 0, v242, s[68:69]
	v_addc_co_u32_e64 v242, s[70:71], 0, v242, s[70:71]
	v_addc_co_u32_e64 v242, s[72:73], 0, v242, s[72:73]
	v_cmp_ge_u32_e64 s[40:41], v232, vcc_lo
	v_cmp_ge_u32_e64 s[42:43], v230, vcc_lo
	v_cmp_ge_u32_e64 s[62:63], v229, vcc_lo
	v_cmp_ge_u32_e64 s[64:65], v228, vcc_lo
	v_cmp_ge_u32_e64 s[66:67], v227, vcc_lo
	v_cmp_ge_u32_e64 s[68:69], v226, vcc_lo
	v_cmp_ge_u32_e64 s[70:71], v225, vcc_lo
	v_cmp_ge_u32_e64 s[72:73], v223, vcc_lo
	v_addc_co_u32_e64 v242, s[40:41], 0, v242, s[40:41]
	v_addc_co_u32_e64 v242, s[42:43], 0, v242, s[42:43]
	v_addc_co_u32_e64 v242, s[62:63], 0, v242, s[62:63]
	v_addc_co_u32_e64 v242, s[64:65], 0, v242, s[64:65]
	v_addc_co_u32_e64 v242, s[66:67], 0, v242, s[66:67]
	v_addc_co_u32_e64 v242, s[68:69], 0, v242, s[68:69]
	v_addc_co_u32_e64 v242, s[70:71], 0, v242, s[70:71]
	v_addc_co_u32_e64 v242, s[72:73], 0, v242, s[72:73]
	s_nop 1
	v_add_u32_dpp v242, v242, v242 row_shr:1 row_mask:0xf bank_mask:0xf bound_ctrl:1
	s_nop 1
	v_add_u32_dpp v242, v242, v242 row_shr:2 row_mask:0xf bank_mask:0xf bound_ctrl:1
	s_nop 1
	v_add_u32_dpp v242, v242, v242 row_shr:4 row_mask:0xf bank_mask:0xf bound_ctrl:1
	s_nop 1
	v_add_u32_dpp v242, v242, v242 row_shr:8 row_mask:0xf bank_mask:0xf bound_ctrl:1
	s_nop 0
	v_readlane_b32 s40, v242, 15
	v_readlane_b32 s41, v242, 31
	s_add_i32 s40, s41, s40
	v_readlane_b32 s41, v242, 47
	s_add_i32 s40, s40, s41
	v_readlane_b32 s41, v242, 63
	s_add_i32 s40, s40, s41
	s_cmpk_gt_i32 s40, 0xff
	s_cselect_b32 s59, s40, s59
	s_cselect_b32 s101, vcc_lo, s101
	s_cmpk_eq_i32 s40, 0x100
	s_cbranch_scc1 .Lselq5_exit
	s_lshr_b32 vcc_hi, vcc_hi, 1
	s_cmp_lg_u32 vcc_hi, 0
	s_cbranch_scc1 .Lselq5_top

; __device__ __forceinline__ void select_group(unsigned char* ws, int r0, const bf16_t* __restrict__ kib, int n, float* sc, SelPre& pre, int nr0, const bf16_t* __restrict__ nkib, int nn) {
;     ...
; #pragma unroll
;     for (int i = 0; i < 64; ++i) {
;       const unsigned ub = __float_as_uint(rowl[i * 64]);
;       const unsigned o = ub ^ ((unsigned)((int)ub >> 31) | 0x80000000u);
;       x[i] = (i * 64 < nl) ? o : 0u;
;     }
;     unsigned tau = 0u;
;     int cge = 0;
;     switch ((nreg + 7) >> 3) {
;       case 1: bisect256<1>(x, tau, cge); break;
;       case 2: bisect256<2>(x, tau, cge); break;
;       case 3: bisect256<3>(x, tau, cge); break;
;       case 4: bisect256<4>(x, tau, cge); break;
;       case 5: bisect256<5>(x, tau, cge); break;
;       case 6: bisect256<6>(x, tau, cge); break;
;       case 7: bisect256<7>(x, tau, cge); break;
;       default: bisect256<8>(x, tau, cge); break;
.LBB0_2967:
	s_waitcnt lgkmcnt(3)
	v_ashrrev_i32_e32 v240, 31, v170
	v_bitop3_b32 v170, v240, v170, s58 bitop3:0x36
	v_cndmask_b32_e64 v243, 0, v170, s[12:13]
	v_ashrrev_i32_e32 v170, 31, v171
	v_bitop3_b32 v170, v170, v171, s58 bitop3:0x36
	v_cndmask_b32_e64 v242, 0, v170, s[6:7]
	s_waitcnt lgkmcnt(2)
	v_ashrrev_i32_e32 v170, 31, v168
	v_bitop3_b32 v168, v170, v168, s58 bitop3:0x36
	v_cndmask_b32_e64 v241, 0, v168, s[8:9]
	v_ashrrev_i32_e32 v168, 31, v169
	v_bitop3_b32 v168, v168, v169, s58 bitop3:0x36
	v_cndmask_b32_e64 v240, 0, v168, s[2:3]
	s_waitcnt lgkmcnt(1)
	v_ashrrev_i32_e32 v168, 31, v166
	v_bitop3_b32 v166, v168, v166, s58 bitop3:0x36
	v_cndmask_b32_e64 v171, 0, v166, s[4:5]
	v_ashrrev_i32_e32 v166, 31, v167
	v_bitop3_b32 v166, v166, v167, s58 bitop3:0x36
	v_cndmask_b32_e64 v170, 0, v166, s[0:1]
	s_waitcnt lgkmcnt(0)
	v_ashrrev_i32_e32 v166, 31, v164
	v_bitop3_b32 v164, v166, v164, s58 bitop3:0x36
	v_cndmask_b32_e64 v169, 0, v164, s[14:15]
	v_ashrrev_i32_e32 v164, 31, v165
	v_bitop3_b32 v164, v164, v165, s58 bitop3:0x36
	v_cndmask_b32_e64 v168, 0, v164, s[10:11]
	s_and_b64 vcc, exec, s[38:39]
	s_cbranch_vccz .LBB0_2971
	s_mov_b32 s59, 0
	s_mov_b32 s101, 0
	s_mov_b32 vcc_hi, 0x80000000
; template <int NB>
; __device__ __forceinline__ void bisect256(const unsigned (&x)[64], unsigned& tau_out, int& cge_out) {
;   unsigned tau = 0u;
;   int cge = 0;
;     ...
;     const unsigned cand = tau | (1u << bit);
;     unsigned cl = 0u;
; #pragma unroll
;     for (int blk = 0; blk < NB; ++blk) {
;       unsigned long long m0, m1, m2, m3, m4, m5, m6, m7;
;       asm volatile(
;           "v_cmp_ge_u32_e64 %1, %9, %17\n\tv_cmp_ge_u32_e64 %2, %10, %17\n\tv_cmp_ge_u32_e64 %3, %11, %17\n\tv_cmp_ge_u32_e64 %4, %12, %17\n\t"
;           "v_cmp_ge_u32_e64 %5, %13, %17\n\tv_cmp_ge_u32_e64 %6, %14, %17\n\tv_cmp_ge_u32_e64 %7, %15, %17\n\tv_cmp_ge_u32_e64 %8, %16, %17\n\t"
;           "v_addc_co_u32_e64 %0, %1, 0, %0, %1\n\tv_addc_co_u32_e64 %0, %2, 0, %0, %2\n\tv_addc_co_u32_e64 %0, %3, 0, %0, %3\n\t"
;           "v_addc_co_u32_e64 %0, %4, 0, %0, %4\n\tv_addc_co_u32_e64 %0, %5, 0, %0, %5\n\tv_addc_co_u32_e64 %0, %6, 0, %0, %6\n\t"
;           "v_addc_co_u32_e64 %0, %7, 0, %0, %7\n\tv_addc_co_u32_e64 %0, %8, 0, %0, %8"
;           : "+v"(cl), "=&s"(m0), "=&s"(m1), "=&s"(m2), "=&s"(m3), "=&s"(m4), "=&s"(m5), "=&s"(m6), "=&s"(m7)
;           : "v"(x[blk * 8 + 0]), "v"(x[blk * 8 + 1]), "v"(x[blk * 8 + 2]), "v"(x[blk * 8 + 3]), "v"(x[blk * 8 + 4]), "v"(x[blk * 8 + 5]),
;             "v"(x[blk * 8 + 6]), "v"(x[blk * 8 + 7]), "v"(cand));
;     }
;     cl += (unsigned)__builtin_amdgcn_update_dpp(0, (int)cl, 0x111, 0xf, 0xf, true);
;     cl += (unsigned)__builtin_amdgcn_update_dpp(0, (int)cl, 0x112, 0xf, 0xf, true);
;     cl += (unsigned)__builtin_amdgcn_update_dpp(0, (int)cl, 0x114, 0xf, 0xf, true);
;     cl += (unsigned)__builtin_amdgcn_update_dpp(0, (int)cl, 0x118, 0xf, 0xf, true);
;     const int cnt = __builtin_amdgcn_readlane((int)cl, 15) + __builtin_amdgcn_readlane((int)cl, 31) + __builtin_amdgcn_readlane((int)cl, 47) +
;                     __builtin_amdgcn_readlane((int)cl, 63);
;     if (cnt >= 256) { tau = cand; cge = cnt; }
;     if (cnt == 256) break;
;   }
.Lselq6_top:
	s_or_b32 vcc_lo, s101, vcc_hi
	v_mov_b32_e32 v166, v17
	v_cmp_ge_u32_e64 s[0:1], v239, vcc_lo
	v_cmp_ge_u32_e64 s[2:3], v238, vcc_lo
	v_cmp_ge_u32_e64 s[4:5], v237, vcc_lo
	v_cmp_ge_u32_e64 s[6:7], v236, vcc_lo
	v_cmp_ge_u32_e64 s[8:9], v235, vcc_lo
	v_cmp_ge_u32_e64 s[10:11], v234, vcc_lo
	v_cmp_ge_u32_e64 s[12:13], v233, vcc_lo
	v_cmp_ge_u32_e64 s[14:15], v231, vcc_lo
	v_addc_co_u32_e64 v166, s[0:1], 0, v166, s[0:1]
	v_addc_co_u32_e64 v166, s[2:3], 0, v166, s[2:3]
	v_addc_co_u32_e64 v166, s[4:5], 0, v166, s[4:5]
	v_addc_co_u32_e64 v166, s[6:7], 0, v166, s[6:7]
	v_addc_co_u32_e64 v166, s[8:9], 0, v166, s[8:9]
	v_addc_co_u32_e64 v166, s[10:11], 0, v166, s[10:11]
	v_addc_co_u32_e64 v166, s[12:13], 0, v166, s[12:13]
	v_addc_co_u32_e64 v166, s[14:15], 0, v166, s[14:15]
	v_cmp_ge_u32_e64 s[0:1], v232, vcc_lo
	v_cmp_ge_u32_e64 s[2:3], v230, vcc_lo
	v_cmp_ge_u32_e64 s[4:5], v229, vcc_lo
	v_cmp_ge_u32_e64 s[6:7], v228, vcc_lo
	v_cmp_ge_u32_e64 s[8:9], v227, vcc_lo
	v_cmp_ge_u32_e64 s[10:11], v226, vcc_lo
	v_cmp_ge_u32_e64 s[12:13], v225, vcc_lo
	v_cmp_ge_u32_e64 s[14:15], v223, vcc_lo
	v_addc_co_u32_e64 v166, s[0:1], 0, v166, s[0:1]
	v_addc_co_u32_e64 v166, s[2:3], 0, v166, s[2:3]
	v_addc_co_u32_e64 v166, s[4:5], 0, v166, s[4:5]
	v_addc_co_u32_e64 v166, s[6:7], 0, v166, s[6:7]
	v_addc_co_u32_e64 v166, s[8:9], 0, v166, s[8:9]
	v_addc_co_u32_e64 v166, s[10:11], 0, v166, s[10:11]
	v_addc_co_u32_e64 v166, s[12:13], 0, v166, s[12:13]
	v_addc_co_u32_e64 v166, s[14:15], 0, v166, s[14:15]
	v_cmp_ge_u32_e64 s[0:1], v224, vcc_lo
	v_cmp_ge_u32_e64 s[2:3], v222, vcc_lo
	v_cmp_ge_u32_e64 s[4:5], v221, vcc_lo
	v_cmp_ge_u32_e64 s[6:7], v220, vcc_lo
	v_cmp_ge_u32_e64 s[8:9], v219, vcc_lo
	v_cmp_ge_u32_e64 s[10:11], v218, vcc_lo
	v_cmp_ge_u32_e64 s[12:13], v217, vcc_lo
	v_cmp_ge_u32_e64 s[14:15], v215, vcc_lo
	v_addc_co_u32_e64 v166, s[0:1], 0, v166, s[0:1]
	v_addc_co_u32_e64 v166, s[2:3], 0, v166, s[2:3]
	v_addc_co_u32_e64 v166, s[4:5], 0, v166, s[4:5]
	v_addc_co_u32_e64 v166, s[6:7], 0, v166, s[6:7]
	v_addc_co_u32_e64 v166, s[8:9], 0, v166, s[8:9]
	v_addc_co_u32_e64 v166, s[10:11], 0, v166, s[10:11]
	v_addc_co_u32_e64 v166, s[12:13], 0, v166, s[12:13]
	v_addc_co_u32_e64 v166, s[14:15], 0, v166, s[14:15]
	v_cmp_ge_u32_e64 s[0:1], v216, vcc_lo
	v_cmp_ge_u32_e64 s[2:3], v214, vcc_lo
	v_cmp_ge_u32_e64 s[4:5], v213, vcc_lo
	v_cmp_ge_u32_e64 s[6:7], v212, vcc_lo
	v_cmp_ge_u32_e64 s[8:9], v211, vcc_lo
	v_cmp_ge_u32_e64 s[10:11], v210, vcc_lo
	v_cmp_ge_u32_e64 s[12:13], v207, vcc_lo
	v_cmp_ge_u32_e64 s[14:15], v194, vcc_lo
	v_addc_co_u32_e64 v166, s[0:1], 0, v166, s[0:1]
	v_addc_co_u32_e64 v166, s[2:3], 0, v166, s[2:3]
	v_addc_co_u32_e64 v166, s[4:5], 0, v166, s[4:5]
	v_addc_co_u32_e64 v166, s[6:7], 0, v166, s[6:7]
	v_addc_co_u32_e64 v166, s[8:9], 0, v166, s[8:9]
	v_addc_co_u32_e64 v166, s[10:11], 0, v166, s[10:11]
	v_addc_co_u32_e64 v166, s[12:13], 0, v166, s[12:13]
	v_addc_co_u32_e64 v166, s[14:15], 0, v166, s[14:15]
	v_cmp_ge_u32_e64 s[0:1], v195, vcc_lo
	v_cmp_ge_u32_e64 s[2:3], v193, vcc_lo
	v_cmp_ge_u32_e64 s[4:5], v192, vcc_lo
	v_cmp_ge_u32_e64 s[6:7], v191, vcc_lo
	v_cmp_ge_u32_e64 s[8:9], v190, vcc_lo
	v_cmp_ge_u32_e64 s[10:11], v189, vcc_lo
	v_cmp_ge_u32_e64 s[12:13], v188, vcc_lo
	v_cmp_ge_u32_e64 s[14:15], v186, vcc_lo
	v_addc_co_u32_e64 v166, s[0:1], 0, v166, s[0:1]
	v_addc_co_u32_e64 v166, s[2:3], 0, v166, s[2:3]
	v_addc_co_u32_e64 v166, s[4:5], 0, v166, s[4:5]
	v_addc_co_u32_e64 v166, s[6:7], 0, v166, s[6:7]
	v_addc_co_u32_e64 v166, s[8:9], 0, v166, s[8:9]
	v_addc_co_u32_e64 v166, s[10:11], 0, v166, s[10:11]
	v_addc_co_u32_e64 v166, s[12:13], 0, v166, s[12:13]
	v_addc_co_u32_e64 v166, s[14:15], 0, v166, s[14:15]
	v_cmp_ge_u32_e64 s[0:1], v187, vcc_lo
	v_cmp_ge_u32_e64 s[2:3], v185, vcc_lo
	v_cmp_ge_u32_e64 s[4:5], v184, vcc_lo
	v_cmp_ge_u32_e64 s[6:7], v183, vcc_lo
	v_cmp_ge_u32_e64 s[8:9], v182, vcc_lo
	v_cmp_ge_u32_e64 s[10:11], v181, vcc_lo
	v_cmp_ge_u32_e64 s[12:13], v180, vcc_lo
	v_cmp_ge_u32_e64 s[14:15], v178, vcc_lo
	v_addc_co_u32_e64 v166, s[0:1], 0, v166, s[0:1]
	v_addc_co_u32_e64 v166, s[2:3], 0, v166, s[2:3]
	v_addc_co_u32_e64 v166, s[4:5], 0, v166, s[4:5]
	v_addc_co_u32_e64 v166, s[6:7], 0, v166, s[6:7]
	v_addc_co_u32_e64 v166, s[8:9], 0, v166, s[8:9]
	v_addc_co_u32_e64 v166, s[10:11], 0, v166, s[10:11]
	v_addc_co_u32_e64 v166, s[12:13], 0, v166, s[12:13]
	v_addc_co_u32_e64 v166, s[14:15], 0, v166, s[14:15]
	v_cmp_ge_u32_e64 s[0:1], v179, vcc_lo
	v_cmp_ge_u32_e64 s[2:3], v177, vcc_lo
	v_cmp_ge_u32_e64 s[4:5], v176, vcc_lo
	v_cmp_ge_u32_e64 s[6:7], v175, vcc_lo
	v_cmp_ge_u32_e64 s[8:9], v174, vcc_lo
	v_cmp_ge_u32_e64 s[10:11], v173, vcc_lo
	v_cmp_ge_u32_e64 s[12:13], v172, vcc_lo
	v_cmp_ge_u32_e64 s[14:15], v115, vcc_lo
	v_addc_co_u32_e64 v166, s[0:1], 0, v166, s[0:1]
	v_addc_co_u32_e64 v166, s[2:3], 0, v166, s[2:3]
	v_addc_co_u32_e64 v166, s[4:5], 0, v166, s[4:5]
	v_addc_co_u32_e64 v166, s[6:7], 0, v166, s[6:7]
	v_addc_co_u32_e64 v166, s[8:9], 0, v166, s[8:9]
	v_addc_co_u32_e64 v166, s[10:11], 0, v166, s[10:11]
	v_addc_co_u32_e64 v166, s[12:13], 0, v166, s[12:13]
	v_addc_co_u32_e64 v166, s[14:15], 0, v166, s[14:15]
	v_cmp_ge_u32_e64 s[0:1], v243, vcc_lo
	v_cmp_ge_u32_e64 s[2:3], v242, vcc_lo
	v_cmp_ge_u32_e64 s[4:5], v241, vcc_lo
	v_cmp_ge_u32_e64 s[6:7], v240, vcc_lo
	v_cmp_ge_u32_e64 s[8:9], v171, vcc_lo
	v_cmp_ge_u32_e64 s[10:11], v170, vcc_lo
	v_cmp_ge_u32_e64 s[12:13], v169, vcc_lo
	v_cmp_ge_u32_e64 s[14:15], v168, vcc_lo
	v_addc_co_u32_e64 v166, s[0:1], 0, v166, s[0:1]
	v_addc_co_u32_e64 v166, s[2:3], 0, v166, s[2:3]
	v_addc_co_u32_e64 v166, s[4:5], 0, v166, s[4:5]
	v_addc_co_u32_e64 v166, s[6:7], 0, v166, s[6:7]
	v_addc_co_u32_e64 v166, s[8:9], 0, v166, s[8:9]
	v_addc_co_u32_e64 v166, s[10:11], 0, v166, s[10:11]
	v_addc_co_u32_e64 v166, s[12:13], 0, v166, s[12:13]
	v_addc_co_u32_e64 v166, s[14:15], 0, v166, s[14:15]
	s_nop 1
	v_add_u32_dpp v166, v166, v166 row_shr:1 row_mask:0xf bank_mask:0xf bound_ctrl:1
	s_nop 1
	v_add_u32_dpp v166, v166, v166 row_shr:2 row_mask:0xf bank_mask:0xf bound_ctrl:1
	s_nop 1
	v_add_u32_dpp v166, v166, v166 row_shr:4 row_mask:0xf bank_mask:0xf bound_ctrl:1
	s_nop 1
	v_add_u32_dpp v166, v166, v166 row_shr:8 row_mask:0xf bank_mask:0xf bound_ctrl:1
	s_nop 0
	v_readlane_b32 s0, v166, 15
	v_readlane_b32 s1, v166, 31
	s_add_i32 s0, s1, s0
	v_readlane_b32 s1, v166, 47
	s_add_i32 s0, s0, s1
	v_readlane_b32 s1, v166, 63
	s_add_i32 s0, s0, s1
	s_cmpk_gt_i32 s0, 0xff
	s_cselect_b32 s59, s0, s59
	s_cselect_b32 s101, vcc_lo, s101
	s_cmpk_eq_i32 s0, 0x100
	s_cbranch_scc1 .Lselq6_exit
	s_lshr_b32 vcc_hi, vcc_hi, 1
	s_cmp_lg_u32 vcc_hi, 0
	s_cbranch_scc1 .Lselq6_top

; template <int NB>
; __device__ __forceinline__ void bisect256(const unsigned (&x)[64], unsigned& tau_out, int& cge_out) {
;   unsigned tau = 0u;
;   int cge = 0;
;     ...
;     const unsigned cand = tau | (1u << bit);
;     unsigned cl = 0u;
; #pragma unroll
;     for (int blk = 0; blk < NB; ++blk) {
;       unsigned long long m0, m1, m2, m3, m4, m5, m6, m7;
;       asm volatile(
;           "v_cmp_ge_u32_e64 %1, %9, %17\n\tv_cmp_ge_u32_e64 %2, %10, %17\n\tv_cmp_ge_u32_e64 %3, %11, %17\n\tv_cmp_ge_u32_e64 %4, %12, %17\n\t"
;           "v_cmp_ge_u32_e64 %5, %13, %17\n\tv_cmp_ge_u32_e64 %6, %14, %17\n\tv_cmp_ge_u32_e64 %7, %15, %17\n\tv_cmp_ge_u32_e64 %8, %16, %17\n\t"
;           "v_addc_co_u32_e64 %0, %1, 0, %0, %1\n\tv_addc_co_u32_e64 %0, %2, 0, %0, %2\n\tv_addc_co_u32_e64 %0, %3, 0, %0, %3\n\t"
;           "v_addc_co_u32_e64 %0, %4, 0, %0, %4\n\tv_addc_co_u32_e64 %0, %5, 0, %0, %5\n\tv_addc_co_u32_e64 %0, %6, 0, %0, %6\n\t"
;           "v_addc_co_u32_e64 %0, %7, 0, %0, %7\n\tv_addc_co_u32_e64 %0, %8, 0, %0, %8"
;           : "+v"(cl), "=&s"(m0), "=&s"(m1), "=&s"(m2), "=&s"(m3), "=&s"(m4), "=&s"(m5), "=&s"(m6), "=&s"(m7)
;           : "v"(x[blk * 8 + 0]), "v"(x[blk * 8 + 1]), "v"(x[blk * 8 + 2]), "v"(x[blk * 8 + 3]), "v"(x[blk * 8 + 4]), "v"(x[blk * 8 + 5]),
;             "v"(x[blk * 8 + 6]), "v"(x[blk * 8 + 7]), "v"(cand));
;     }
;     cl += (unsigned)__builtin_amdgcn_update_dpp(0, (int)cl, 0x111, 0xf, 0xf, true);
;     cl += (unsigned)__builtin_amdgcn_update_dpp(0, (int)cl, 0x112, 0xf, 0xf, true);
;     cl += (unsigned)__builtin_amdgcn_update_dpp(0, (int)cl, 0x114, 0xf, 0xf, true);
;     cl += (unsigned)__builtin_amdgcn_update_dpp(0, (int)cl, 0x118, 0xf, 0xf, true);
;     const int cnt = __builtin_amdgcn_readlane((int)cl, 15) + __builtin_amdgcn_readlane((int)cl, 31) + __builtin_amdgcn_readlane((int)cl, 47) +
;                     __builtin_amdgcn_readlane((int)cl, 63);
;     if (cnt >= 256) { tau = cand; cge = cnt; }
;     if (cnt == 256) break;
;   }
.LBB0_2971:
	s_and_b64 vcc, exec, s[40:41]
	s_cbranch_vccz .LBB0_2974
	s_mov_b32 s59, 0
	s_mov_b32 s101, 0
	s_mov_b32 vcc_hi, 0x80000000
.Lselq7_top:
	s_or_b32 vcc_lo, s101, vcc_hi
	v_mov_b32_e32 v166, v17
	v_cmp_ge_u32_e64 s[0:1], v239, vcc_lo
	v_cmp_ge_u32_e64 s[2:3], v238, vcc_lo
	v_cmp_ge_u32_e64 s[4:5], v237, vcc_lo
	v_cmp_ge_u32_e64 s[6:7], v236, vcc_lo
	v_cmp_ge_u32_e64 s[8:9], v235, vcc_lo
	v_cmp_ge_u32_e64 s[10:11], v234, vcc_lo
	v_cmp_ge_u32_e64 s[12:13], v233, vcc_lo
	v_cmp_ge_u32_e64 s[14:15], v231, vcc_lo
	v_addc_co_u32_e64 v166, s[0:1], 0, v166, s[0:1]
	v_addc_co_u32_e64 v166, s[2:3], 0, v166, s[2:3]
	v_addc_co_u32_e64 v166, s[4:5], 0, v166, s[4:5]
	v_addc_co_u32_e64 v166, s[6:7], 0, v166, s[6:7]
	v_addc_co_u32_e64 v166, s[8:9], 0, v166, s[8:9]
	v_addc_co_u32_e64 v166, s[10:11], 0, v166, s[10:11]
	v_addc_co_u32_e64 v166, s[12:13], 0, v166, s[12:13]
	v_addc_co_u32_e64 v166, s[14:15], 0, v166, s[14:15]
	s_nop 1
	v_add_u32_dpp v166, v166, v166 row_shr:1 row_mask:0xf bank_mask:0xf bound_ctrl:1
	s_nop 1
	v_add_u32_dpp v166, v166, v166 row_shr:2 row_mask:0xf bank_mask:0xf bound_ctrl:1
	s_nop 1
	v_add_u32_dpp v166, v166, v166 row_shr:4 row_mask:0xf bank_mask:0xf bound_ctrl:1
	s_nop 1
	v_add_u32_dpp v166, v166, v166 row_shr:8 row_mask:0xf bank_mask:0xf bound_ctrl:1
	s_nop 0
	v_readlane_b32 s0, v166, 15
	v_readlane_b32 s1, v166, 31
	s_add_i32 s0, s1, s0
	v_readlane_b32 s1, v166, 47
	s_add_i32 s0, s0, s1
	v_readlane_b32 s1, v166, 63
	s_add_i32 s0, s0, s1
	s_cmpk_gt_i32 s0, 0xff
	s_cselect_b32 s59, s0, s59
	s_cselect_b32 s101, vcc_lo, s101
	s_cmpk_eq_i32 s0, 0x100
	s_cbranch_scc1 .Lselq7_exit
	s_lshr_b32 vcc_hi, vcc_hi, 1
	s_cmp_lg_u32 vcc_hi, 0
	s_cbranch_scc1 .Lselq7_top
